# sg_post: all 24 row loads issued up front with counted waits (on top of pipelined post_attn)
# baseline (speedup 1.0000x reference)
.LBB0_1103:
	s_andn2_b64 vcc, exec, s[0:1]
	s_cbranch_vccnz .LBB0_1092
	v_mov_b32_e32 v4, v232
	s_add_i32 s96, s8, 0xfffdc000
	v_ashrrev_i32_e32 v0, 3, v4
	v_and_b32_e32 v0, -8, v0
	v_ashrrev_i32_e32 v1, 31, v0
	v_lshl_add_u64 v[0:1], v[0:1], 0, s[96:97]
	v_mov_b64_e32 v[2:3], s[82:83]
	s_movk_i32 s2, 0x3800
	v_mad_u64_u32 v[2:3], s[0:1], v0, s2, v[2:3]
	v_lshlrev_b32_e32 v0, 4, v4
	v_mad_i32_i24 v3, v1, s2, v3
	v_and_b32_e32 v16, 0x3f0, v0
	v_lshl_add_u64 v[14:15], v[2:3], 0, v[16:17]
	v_add_co_u32_e32 v4, vcc, s77, v14
	s_mov_b32 s0, 0xbf3a00e3
	s_nop 0
	v_addc_co_u32_e32 v5, vcc, 0, v15, vcc
	v_mov_b64_e32 v[32:33], v[14:15]
	s_mov_b64 s[12:13], 0x2000
	v_lshl_add_u64 v[34:35], v[14:15], 0, s[12:13]
	global_load_dwordx4 v[36:39], v[34:35], off offset:1536
	global_load_dwordx4 v[40:43], v[34:35], off offset:2560
	global_load_dwordx4 v[44:47], v[32:33], off offset:2048
	s_mov_b64 s[12:13], 0x3800
	v_lshl_add_u64 v[32:33], v[14:15], 0, s[12:13]
	s_mov_b64 s[12:13], 0x5800
	v_lshl_add_u64 v[34:35], v[14:15], 0, s[12:13]
	global_load_dwordx4 v[48:51], v[34:35], off offset:1536
	global_load_dwordx4 v[52:55], v[34:35], off offset:2560
	global_load_dwordx4 v[56:59], v[32:33], off offset:2048
	s_mov_b64 s[12:13], 0x7000
	v_lshl_add_u64 v[32:33], v[14:15], 0, s[12:13]
	s_mov_b64 s[12:13], 0x9000
	v_lshl_add_u64 v[34:35], v[14:15], 0, s[12:13]
	global_load_dwordx4 v[60:63], v[34:35], off offset:1536
	global_load_dwordx4 v[64:67], v[34:35], off offset:2560
	global_load_dwordx4 v[68:71], v[32:33], off offset:2048
	s_mov_b64 s[12:13], 0xa800
	v_lshl_add_u64 v[32:33], v[14:15], 0, s[12:13]
	s_mov_b64 s[12:13], 0xc800
	v_lshl_add_u64 v[34:35], v[14:15], 0, s[12:13]
	global_load_dwordx4 v[72:75], v[34:35], off offset:1536
	global_load_dwordx4 v[76:79], v[34:35], off offset:2560
	global_load_dwordx4 v[80:83], v[32:33], off offset:2048
	s_mov_b64 s[12:13], 0xe000
	v_lshl_add_u64 v[32:33], v[14:15], 0, s[12:13]
	s_mov_b64 s[12:13], 0x10000
	v_lshl_add_u64 v[34:35], v[14:15], 0, s[12:13]
	global_load_dwordx4 v[84:87], v[34:35], off offset:1536
	global_load_dwordx4 v[88:91], v[34:35], off offset:2560
	global_load_dwordx4 v[92:95], v[32:33], off offset:2048
	s_mov_b64 s[12:13], 0x11800
	v_lshl_add_u64 v[32:33], v[14:15], 0, s[12:13]
	s_mov_b64 s[12:13], 0x13800
	v_lshl_add_u64 v[34:35], v[14:15], 0, s[12:13]
	global_load_dwordx4 v[96:99], v[34:35], off offset:1536
	global_load_dwordx4 v[100:103], v[34:35], off offset:2560
	global_load_dwordx4 v[104:107], v[32:33], off offset:2048
	s_mov_b64 s[12:13], 0x15000
	v_lshl_add_u64 v[32:33], v[14:15], 0, s[12:13]
	s_mov_b64 s[12:13], 0x17000
	v_lshl_add_u64 v[34:35], v[14:15], 0, s[12:13]
	global_load_dwordx4 v[108:111], v[34:35], off offset:1536
	global_load_dwordx4 v[112:115], v[34:35], off offset:2560
	global_load_dwordx4 v[116:119], v[32:33], off offset:2048
	s_mov_b64 s[12:13], 0x18800
	v_lshl_add_u64 v[32:33], v[14:15], 0, s[12:13]
	s_mov_b64 s[12:13], 0x1a800
	v_lshl_add_u64 v[34:35], v[14:15], 0, s[12:13]
	global_load_dwordx4 v[120:123], v[34:35], off offset:1536
	global_load_dwordx4 v[124:127], v[34:35], off offset:2560
	global_load_dwordx4 v[128:131], v[32:33], off offset:2048
	s_waitcnt vmcnt(21)
	v_mov_b64_e32 v[0:1], v[36:37]
	v_mov_b64_e32 v[2:3], v[38:39]
	s_nop 0
	v_mov_b64_e32 v[4:5], v[40:41]
	v_mov_b64_e32 v[6:7], v[42:43]
	s_nop 0
	v_mov_b64_e32 v[8:9], v[44:45]
	v_mov_b64_e32 v[10:11], v[46:47]
	v_mov_b64_e32 v[12:13], s[0:1]
	v_lshlrev_b32_e32 v18, 16, v0
	v_and_b32_e32 v19, 0xffff0000, v0
	v_fma_f32 v0, |v18|, s85, 1.0
	v_pk_mul_f32 v[26:27], v[18:19], v[18:19]
	v_lshlrev_b32_e32 v22, 16, v8
	v_rcp_f32_e32 v24, v0
	v_mul_f32_e32 v0, 0xbf38aa3b, v26
	v_exp_f32_e32 v26, v0
	v_mul_f32_e32 v0, 0xbfb8aa3b, v22
	v_exp_f32_e32 v0, v0
	v_and_b32_e32 v23, 0xffff0000, v8
	v_cmp_gt_f32_e32 vcc, 0, v18
	v_cmp_gt_f32_e64 s[0:1], 0, v19
	v_add_f32_e32 v0, 1.0, v0
	v_rcp_f32_e32 v28, v0
	v_fma_f32 v0, |v19|, s85, 1.0
	v_rcp_f32_e32 v25, v0
	v_mul_f32_e32 v0, 0xbf38aa3b, v27
	v_exp_f32_e32 v27, v0
	v_mul_f32_e32 v0, 0xbfb8aa3b, v23
	v_exp_f32_e32 v0, v0
	v_pk_fma_f32 v[30:31], v[24:25], s[74:75], v[12:13] op_sel_hi:[1,0,0]
	v_lshlrev_b32_e32 v20, 16, v4
	v_pk_fma_f32 v[30:31], v[24:25], v[30:31], s[84:85] op_sel_hi:[1,1,0]
	v_add_f32_e32 v0, 1.0, v0
	v_pk_fma_f32 v[30:31], v[24:25], v[30:31], s[86:87] op_sel_hi:[1,1,0]
	v_rcp_f32_e32 v29, v0
	v_pk_fma_f32 v[30:31], v[24:25], v[30:31], s[24:25] op_sel_hi:[1,1,0]
	v_and_b32_e32 v21, 0xffff0000, v4
	v_pk_mul_f32 v[24:25], v[24:25], v[30:31]
	v_lshlrev_b32_e32 v8, 16, v9
	v_pk_mul_f32 v[24:25], v[26:27], v[24:25]
	v_and_b32_e32 v9, 0xffff0000, v9
	v_pk_mul_f32 v[26:27], v[24:25], v[18:19]
	v_pk_fma_f32 v[18:19], v[24:25], v[18:19], v[18:19] neg_lo:[1,0,0] neg_hi:[1,0,0]
	v_lshlrev_b32_e32 v4, 16, v5
	v_cndmask_b32_e64 v19, v19, v27, s[0:1]
	v_cndmask_b32_e32 v18, v18, v26, vcc
	v_pk_mul_f32 v[18:19], v[18:19], v[20:21]
	v_pk_mul_f32 v[20:21], v[28:29], v[22:23]
	v_and_b32_e32 v5, 0xffff0000, v5
	v_pk_mul_f32 v[18:19], v[20:21], v[18:19]
	s_nop 0
	v_cvt_pk_bf16_f32 v0, v18, v19
	v_lshlrev_b32_e32 v18, 16, v1
	v_and_b32_e32 v19, 0xffff0000, v1
	v_fma_f32 v1, |v18|, s85, 1.0
	v_pk_mul_f32 v[22:23], v[18:19], v[18:19]
	v_rcp_f32_e32 v20, v1
	v_mul_f32_e32 v1, 0xbf38aa3b, v22
	v_exp_f32_e32 v22, v1
	v_mul_f32_e32 v1, 0xbfb8aa3b, v8
	v_exp_f32_e32 v1, v1
	v_cmp_gt_f32_e32 vcc, 0, v18
	v_cmp_gt_f32_e64 s[0:1], 0, v19
	v_add_f32_e32 v1, 1.0, v1
	v_rcp_f32_e32 v24, v1
	v_fma_f32 v1, |v19|, s85, 1.0
	v_rcp_f32_e32 v21, v1
	v_mul_f32_e32 v1, 0xbf38aa3b, v23
	v_exp_f32_e32 v23, v1
	v_mul_f32_e32 v1, 0xbfb8aa3b, v9
	v_exp_f32_e32 v1, v1
	v_pk_fma_f32 v[26:27], v[20:21], s[74:75], v[12:13] op_sel_hi:[1,0,0]
	v_add_f32_e32 v1, 1.0, v1
	v_pk_fma_f32 v[26:27], v[20:21], v[26:27], s[84:85] op_sel_hi:[1,1,0]
	v_rcp_f32_e32 v25, v1
	v_pk_fma_f32 v[26:27], v[20:21], v[26:27], s[86:87] op_sel_hi:[1,1,0]
	v_pk_mul_f32 v[8:9], v[24:25], v[8:9]
	v_pk_fma_f32 v[26:27], v[20:21], v[26:27], s[24:25] op_sel_hi:[1,1,0]
	s_nop 0
	v_pk_mul_f32 v[20:21], v[20:21], v[26:27]
	s_nop 0
	v_pk_mul_f32 v[20:21], v[22:23], v[20:21]
	s_nop 0
	v_pk_mul_f32 v[22:23], v[20:21], v[18:19]
	v_pk_fma_f32 v[18:19], v[20:21], v[18:19], v[18:19] neg_lo:[1,0,0] neg_hi:[1,0,0]
	s_nop 0
	v_cndmask_b32_e64 v19, v19, v23, s[0:1]
	v_cndmask_b32_e32 v18, v18, v22, vcc
	v_pk_mul_f32 v[4:5], v[18:19], v[4:5]
	v_lshlrev_b32_e32 v18, 16, v10
	v_pk_mul_f32 v[4:5], v[8:9], v[4:5]
	v_and_b32_e32 v19, 0xffff0000, v10
	v_cvt_pk_bf16_f32 v1, v4, v5
	v_lshlrev_b32_e32 v4, 16, v2
	v_and_b32_e32 v5, 0xffff0000, v2
	v_fma_f32 v2, |v4|, s85, 1.0
	v_pk_mul_f32 v[22:23], v[4:5], v[4:5]
	v_rcp_f32_e32 v20, v2
	v_mul_f32_e32 v2, 0xbf38aa3b, v22
	v_exp_f32_e32 v22, v2
	v_mul_f32_e32 v2, 0xbfb8aa3b, v18
	v_exp_f32_e32 v2, v2
	v_cmp_gt_f32_e32 vcc, 0, v4
	v_cmp_gt_f32_e64 s[0:1], 0, v5
	v_lshlrev_b32_e32 v8, 16, v6
	v_add_f32_e32 v2, 1.0, v2
	v_rcp_f32_e32 v24, v2
	v_fma_f32 v2, |v5|, s85, 1.0
	v_rcp_f32_e32 v21, v2
	v_mul_f32_e32 v2, 0xbf38aa3b, v23
	v_exp_f32_e32 v23, v2
	v_mul_f32_e32 v2, 0xbfb8aa3b, v19
	v_exp_f32_e32 v2, v2
	v_pk_fma_f32 v[26:27], v[20:21], s[74:75], v[12:13] op_sel_hi:[1,0,0]
	v_and_b32_e32 v9, 0xffff0000, v6
	v_pk_fma_f32 v[26:27], v[20:21], v[26:27], s[84:85] op_sel_hi:[1,1,0]
	v_add_f32_e32 v2, 1.0, v2
	v_pk_fma_f32 v[26:27], v[20:21], v[26:27], s[86:87] op_sel_hi:[1,1,0]
	v_rcp_f32_e32 v25, v2
	v_pk_fma_f32 v[26:27], v[20:21], v[26:27], s[24:25] op_sel_hi:[1,1,0]
	v_lshlrev_b32_e32 v6, 16, v7
	v_pk_mul_f32 v[20:21], v[20:21], v[26:27]
	v_and_b32_e32 v7, 0xffff0000, v7
	v_pk_mul_f32 v[20:21], v[22:23], v[20:21]
	s_nop 0
	v_pk_mul_f32 v[22:23], v[20:21], v[4:5]
	v_pk_fma_f32 v[4:5], v[20:21], v[4:5], v[4:5] neg_lo:[1,0,0] neg_hi:[1,0,0]
	s_nop 0
	v_cndmask_b32_e64 v5, v5, v23, s[0:1]
	v_cndmask_b32_e32 v4, v4, v22, vcc
	v_pk_mul_f32 v[4:5], v[4:5], v[8:9]
	v_pk_mul_f32 v[8:9], v[24:25], v[18:19]
	s_nop 0
	v_pk_mul_f32 v[4:5], v[8:9], v[4:5]
	v_lshlrev_b32_e32 v8, 16, v11
	v_cvt_pk_bf16_f32 v2, v4, v5
	v_lshlrev_b32_e32 v4, 16, v3
	v_and_b32_e32 v5, 0xffff0000, v3
	v_fma_f32 v3, |v4|, s85, 1.0
	v_pk_mul_f32 v[18:19], v[4:5], v[4:5]
	v_rcp_f32_e32 v10, v3
	v_mul_f32_e32 v3, 0xbf38aa3b, v18
	v_exp_f32_e32 v18, v3
	v_mul_f32_e32 v3, 0xbfb8aa3b, v8
	v_exp_f32_e32 v3, v3
	v_and_b32_e32 v9, 0xffff0000, v11
	v_cmp_gt_f32_e32 vcc, 0, v4
	v_cmp_gt_f32_e64 s[0:1], 0, v5
	v_add_f32_e32 v3, 1.0, v3
	v_rcp_f32_e32 v20, v3
	v_fma_f32 v3, |v5|, s85, 1.0
	v_rcp_f32_e32 v11, v3
	v_mul_f32_e32 v3, 0xbf38aa3b, v19
	v_exp_f32_e32 v19, v3
	v_mul_f32_e32 v3, 0xbfb8aa3b, v9
	v_exp_f32_e32 v3, v3
	v_pk_fma_f32 v[22:23], v[10:11], s[74:75], v[12:13] op_sel_hi:[1,0,0]
	v_add_f32_e32 v3, 1.0, v3
	v_pk_fma_f32 v[22:23], v[10:11], v[22:23], s[84:85] op_sel_hi:[1,1,0]
	v_rcp_f32_e32 v21, v3
	v_pk_fma_f32 v[22:23], v[10:11], v[22:23], s[86:87] op_sel_hi:[1,1,0]
	s_nop 0
	v_pk_fma_f32 v[22:23], v[10:11], v[22:23], s[24:25] op_sel_hi:[1,1,0]
	s_nop 0
	v_pk_mul_f32 v[10:11], v[10:11], v[22:23]
	s_nop 0
	v_pk_mul_f32 v[10:11], v[18:19], v[10:11]
	s_nop 0
	v_pk_mul_f32 v[18:19], v[10:11], v[4:5]
	v_pk_fma_f32 v[4:5], v[10:11], v[4:5], v[4:5] neg_lo:[1,0,0] neg_hi:[1,0,0]
	s_nop 0
	v_cndmask_b32_e64 v5, v5, v19, s[0:1]
	v_cndmask_b32_e32 v4, v4, v18, vcc
	v_pk_mul_f32 v[4:5], v[4:5], v[6:7]
	v_pk_mul_f32 v[6:7], v[20:21], v[8:9]
	s_movk_i32 s0, 0x5000
	v_pk_mul_f32 v[4:5], v[6:7], v[4:5]
	s_nop 0
	v_cvt_pk_bf16_f32 v3, v4, v5
	global_store_dwordx4 v[14:15], v[0:3], off offset:2048
	s_nop 1
	v_add_co_u32_e32 v0, vcc, s0, v14
	s_movk_i32 s0, 0x4000
	s_nop 0
	v_addc_co_u32_e32 v1, vcc, 0, v15, vcc
	v_add_co_u32_e32 v4, vcc, s95, v14
	s_waitcnt vmcnt(19)
	v_mov_b64_e32 v[0:1], v[48:49]
	v_mov_b64_e32 v[2:3], v[50:51]
	s_nop 0
	v_addc_co_u32_e32 v5, vcc, 0, v15, vcc
	v_add_co_u32_e32 v18, vcc, s0, v14
	v_mov_b64_e32 v[4:5], v[52:53]
	v_mov_b64_e32 v[6:7], v[54:55]
	s_nop 0
	v_addc_co_u32_e32 v19, vcc, 0, v15, vcc
	v_mov_b64_e32 v[8:9], v[56:57]
	v_mov_b64_e32 v[10:11], v[58:59]
	v_lshlrev_b32_e32 v20, 16, v0
	v_and_b32_e32 v21, 0xffff0000, v0
	v_fma_f32 v0, |v20|, s85, 1.0
	v_pk_mul_f32 v[28:29], v[20:21], v[20:21]
	v_rcp_f32_e32 v26, v0
	v_mul_f32_e32 v0, 0xbf38aa3b, v28
	v_exp_f32_e32 v28, v0
	v_cmp_gt_f32_e32 vcc, 0, v20
	v_lshlrev_b32_e32 v24, 16, v8
	v_mul_f32_e32 v0, 0xbfb8aa3b, v24
	v_exp_f32_e32 v0, v0
	v_and_b32_e32 v25, 0xffff0000, v8
	v_cmp_gt_f32_e64 s[0:1], 0, v21
	v_lshlrev_b32_e32 v22, 16, v4
	v_add_f32_e32 v0, 1.0, v0
	v_rcp_f32_e32 v30, v0
	v_fma_f32 v0, |v21|, s85, 1.0
	v_rcp_f32_e32 v27, v0
	v_mul_f32_e32 v0, 0xbf38aa3b, v29
	v_exp_f32_e32 v29, v0
	v_mul_f32_e32 v0, 0xbfb8aa3b, v25
	v_exp_f32_e32 v0, v0
	v_pk_fma_f32 v[32:33], v[26:27], s[74:75], v[12:13] op_sel_hi:[1,0,0]
	v_and_b32_e32 v23, 0xffff0000, v4
	v_pk_fma_f32 v[32:33], v[26:27], v[32:33], s[84:85] op_sel_hi:[1,1,0]
	v_add_f32_e32 v0, 1.0, v0
	v_pk_fma_f32 v[32:33], v[26:27], v[32:33], s[86:87] op_sel_hi:[1,1,0]
	v_rcp_f32_e32 v31, v0
	v_pk_fma_f32 v[32:33], v[26:27], v[32:33], s[24:25] op_sel_hi:[1,1,0]
	v_lshlrev_b32_e32 v8, 16, v9
	v_pk_mul_f32 v[26:27], v[26:27], v[32:33]
	v_and_b32_e32 v9, 0xffff0000, v9
	v_pk_mul_f32 v[26:27], v[28:29], v[26:27]
	v_lshlrev_b32_e32 v4, 16, v5
	v_pk_mul_f32 v[28:29], v[26:27], v[20:21]
	v_pk_fma_f32 v[20:21], v[26:27], v[20:21], v[20:21] neg_lo:[1,0,0] neg_hi:[1,0,0]
	v_and_b32_e32 v5, 0xffff0000, v5
	v_cndmask_b32_e64 v21, v21, v29, s[0:1]
	v_cndmask_b32_e32 v20, v20, v28, vcc
	v_pk_mul_f32 v[20:21], v[20:21], v[22:23]
	v_pk_mul_f32 v[22:23], v[30:31], v[24:25]
	s_nop 0
	v_pk_mul_f32 v[20:21], v[22:23], v[20:21]
	s_nop 0
	v_cvt_pk_bf16_f32 v0, v20, v21
	v_lshlrev_b32_e32 v20, 16, v1
	v_and_b32_e32 v21, 0xffff0000, v1
	v_fma_f32 v1, |v20|, s85, 1.0
	v_pk_mul_f32 v[24:25], v[20:21], v[20:21]
	v_rcp_f32_e32 v22, v1
	v_mul_f32_e32 v1, 0xbf38aa3b, v24
	v_exp_f32_e32 v24, v1
	v_mul_f32_e32 v1, 0xbfb8aa3b, v8
	v_exp_f32_e32 v1, v1
	v_cmp_gt_f32_e32 vcc, 0, v20
	v_cmp_gt_f32_e64 s[0:1], 0, v21
	v_add_f32_e32 v1, 1.0, v1
	v_rcp_f32_e32 v26, v1
	v_fma_f32 v1, |v21|, s85, 1.0
	v_rcp_f32_e32 v23, v1
	v_mul_f32_e32 v1, 0xbf38aa3b, v25
	v_exp_f32_e32 v25, v1
	v_mul_f32_e32 v1, 0xbfb8aa3b, v9
	v_exp_f32_e32 v1, v1
	v_pk_fma_f32 v[28:29], v[22:23], s[74:75], v[12:13] op_sel_hi:[1,0,0]
	v_add_f32_e32 v1, 1.0, v1
	v_pk_fma_f32 v[28:29], v[22:23], v[28:29], s[84:85] op_sel_hi:[1,1,0]
	v_rcp_f32_e32 v27, v1
	v_pk_fma_f32 v[28:29], v[22:23], v[28:29], s[86:87] op_sel_hi:[1,1,0]
	v_pk_mul_f32 v[8:9], v[26:27], v[8:9]
	v_pk_fma_f32 v[28:29], v[22:23], v[28:29], s[24:25] op_sel_hi:[1,1,0]
	s_nop 0
	v_pk_mul_f32 v[22:23], v[22:23], v[28:29]
	s_nop 0
	v_pk_mul_f32 v[22:23], v[24:25], v[22:23]
	s_nop 0
	v_pk_mul_f32 v[24:25], v[22:23], v[20:21]
	v_pk_fma_f32 v[20:21], v[22:23], v[20:21], v[20:21] neg_lo:[1,0,0] neg_hi:[1,0,0]
	s_nop 0
	v_cndmask_b32_e64 v21, v21, v25, s[0:1]
	v_cndmask_b32_e32 v20, v20, v24, vcc
	v_pk_mul_f32 v[4:5], v[20:21], v[4:5]
	v_lshlrev_b32_e32 v20, 16, v10
	v_pk_mul_f32 v[4:5], v[8:9], v[4:5]
	v_and_b32_e32 v21, 0xffff0000, v10
	v_cvt_pk_bf16_f32 v1, v4, v5
	v_lshlrev_b32_e32 v4, 16, v2
	v_and_b32_e32 v5, 0xffff0000, v2
	v_fma_f32 v2, |v4|, s85, 1.0
	v_pk_mul_f32 v[24:25], v[4:5], v[4:5]
	v_rcp_f32_e32 v22, v2
	v_mul_f32_e32 v2, 0xbf38aa3b, v24
	v_exp_f32_e32 v24, v2
	v_mul_f32_e32 v2, 0xbfb8aa3b, v20
	v_exp_f32_e32 v2, v2
	v_cmp_gt_f32_e32 vcc, 0, v4
	v_cmp_gt_f32_e64 s[0:1], 0, v5
	v_lshlrev_b32_e32 v8, 16, v6
	v_add_f32_e32 v2, 1.0, v2
	v_rcp_f32_e32 v26, v2
	v_fma_f32 v2, |v5|, s85, 1.0
	v_rcp_f32_e32 v23, v2
	v_mul_f32_e32 v2, 0xbf38aa3b, v25
	v_exp_f32_e32 v25, v2
	v_mul_f32_e32 v2, 0xbfb8aa3b, v21
	v_exp_f32_e32 v2, v2
	v_pk_fma_f32 v[28:29], v[22:23], s[74:75], v[12:13] op_sel_hi:[1,0,0]
	v_and_b32_e32 v9, 0xffff0000, v6
	v_pk_fma_f32 v[28:29], v[22:23], v[28:29], s[84:85] op_sel_hi:[1,1,0]
	v_add_f32_e32 v2, 1.0, v2
	v_pk_fma_f32 v[28:29], v[22:23], v[28:29], s[86:87] op_sel_hi:[1,1,0]
	v_rcp_f32_e32 v27, v2
	v_pk_fma_f32 v[28:29], v[22:23], v[28:29], s[24:25] op_sel_hi:[1,1,0]
	v_lshlrev_b32_e32 v6, 16, v7
	v_pk_mul_f32 v[22:23], v[22:23], v[28:29]
	v_and_b32_e32 v7, 0xffff0000, v7
	v_pk_mul_f32 v[22:23], v[24:25], v[22:23]
	s_nop 0
	v_pk_mul_f32 v[24:25], v[22:23], v[4:5]
	v_pk_fma_f32 v[4:5], v[22:23], v[4:5], v[4:5] neg_lo:[1,0,0] neg_hi:[1,0,0]
	s_nop 0
	v_cndmask_b32_e64 v5, v5, v25, s[0:1]
	v_cndmask_b32_e32 v4, v4, v24, vcc
	v_pk_mul_f32 v[4:5], v[4:5], v[8:9]
	v_pk_mul_f32 v[8:9], v[26:27], v[20:21]
	s_nop 0
	v_pk_mul_f32 v[4:5], v[8:9], v[4:5]
	v_lshlrev_b32_e32 v8, 16, v11
	v_cvt_pk_bf16_f32 v2, v4, v5
	v_lshlrev_b32_e32 v4, 16, v3
	v_and_b32_e32 v5, 0xffff0000, v3
	v_fma_f32 v3, |v4|, s85, 1.0
	v_pk_mul_f32 v[20:21], v[4:5], v[4:5]
	v_rcp_f32_e32 v10, v3
	v_mul_f32_e32 v3, 0xbf38aa3b, v20
	v_exp_f32_e32 v20, v3
	v_mul_f32_e32 v3, 0xbfb8aa3b, v8
	v_exp_f32_e32 v3, v3
	v_and_b32_e32 v9, 0xffff0000, v11
	v_cmp_gt_f32_e32 vcc, 0, v4
	v_cmp_gt_f32_e64 s[0:1], 0, v5
	v_add_f32_e32 v3, 1.0, v3
	v_rcp_f32_e32 v22, v3
	v_fma_f32 v3, |v5|, s85, 1.0
	v_rcp_f32_e32 v11, v3
	v_mul_f32_e32 v3, 0xbf38aa3b, v21
	v_exp_f32_e32 v21, v3
	v_mul_f32_e32 v3, 0xbfb8aa3b, v9
	v_exp_f32_e32 v3, v3
	v_pk_fma_f32 v[24:25], v[10:11], s[74:75], v[12:13] op_sel_hi:[1,0,0]
	v_add_f32_e32 v3, 1.0, v3
	v_pk_fma_f32 v[24:25], v[10:11], v[24:25], s[84:85] op_sel_hi:[1,1,0]
	v_rcp_f32_e32 v23, v3
	v_pk_fma_f32 v[24:25], v[10:11], v[24:25], s[86:87] op_sel_hi:[1,1,0]
	s_nop 0
	v_pk_fma_f32 v[24:25], v[10:11], v[24:25], s[24:25] op_sel_hi:[1,1,0]
	s_nop 0
	v_pk_mul_f32 v[10:11], v[10:11], v[24:25]
	s_nop 0
	v_pk_mul_f32 v[10:11], v[20:21], v[10:11]
	s_nop 0
	v_pk_mul_f32 v[20:21], v[10:11], v[4:5]
	v_pk_fma_f32 v[4:5], v[10:11], v[4:5], v[4:5] neg_lo:[1,0,0] neg_hi:[1,0,0]
	s_nop 0
	v_cndmask_b32_e64 v5, v5, v21, s[0:1]
	v_cndmask_b32_e32 v4, v4, v20, vcc
	v_pk_mul_f32 v[4:5], v[4:5], v[6:7]
	v_pk_mul_f32 v[6:7], v[22:23], v[8:9]
	s_mov_b32 s0, 0x9000
	v_pk_mul_f32 v[4:5], v[6:7], v[4:5]
	s_nop 0
	v_cvt_pk_bf16_f32 v3, v4, v5
	v_add_co_u32_e32 v4, vcc, s0, v14
	global_store_dwordx4 v[18:19], v[0:3], off
	s_nop 0
	v_addc_co_u32_e32 v5, vcc, 0, v15, vcc
	v_add_co_u32_e32 v18, vcc, s76, v14
	s_waitcnt vmcnt(17)
	v_mov_b64_e32 v[0:1], v[60:61]
	v_mov_b64_e32 v[2:3], v[62:63]
	s_nop 0
	v_mov_b64_e32 v[4:5], v[64:65]
	v_mov_b64_e32 v[6:7], v[66:67]
	v_addc_co_u32_e32 v19, vcc, 0, v15, vcc
	v_mov_b64_e32 v[8:9], v[68:69]
	v_mov_b64_e32 v[10:11], v[70:71]
	v_lshlrev_b32_e32 v20, 16, v0
	v_and_b32_e32 v21, 0xffff0000, v0
	v_fma_f32 v0, |v20|, s85, 1.0
	v_pk_mul_f32 v[28:29], v[20:21], v[20:21]
	v_lshlrev_b32_e32 v24, 16, v8
	v_rcp_f32_e32 v26, v0
	v_mul_f32_e32 v0, 0xbf38aa3b, v28
	v_exp_f32_e32 v28, v0
	v_mul_f32_e32 v0, 0xbfb8aa3b, v24
	v_exp_f32_e32 v0, v0
	v_and_b32_e32 v25, 0xffff0000, v8
	v_cmp_gt_f32_e32 vcc, 0, v20
	v_cmp_gt_f32_e64 s[0:1], 0, v21
	v_add_f32_e32 v0, 1.0, v0
	v_rcp_f32_e32 v30, v0
	v_fma_f32 v0, |v21|, s85, 1.0
	v_rcp_f32_e32 v27, v0
	v_mul_f32_e32 v0, 0xbf38aa3b, v29
	v_exp_f32_e32 v29, v0
	v_mul_f32_e32 v0, 0xbfb8aa3b, v25
	v_exp_f32_e32 v0, v0
	v_pk_fma_f32 v[32:33], v[26:27], s[74:75], v[12:13] op_sel_hi:[1,0,0]
	v_lshlrev_b32_e32 v22, 16, v4
	v_pk_fma_f32 v[32:33], v[26:27], v[32:33], s[84:85] op_sel_hi:[1,1,0]
	v_add_f32_e32 v0, 1.0, v0
	v_pk_fma_f32 v[32:33], v[26:27], v[32:33], s[86:87] op_sel_hi:[1,1,0]
	v_rcp_f32_e32 v31, v0
	v_pk_fma_f32 v[32:33], v[26:27], v[32:33], s[24:25] op_sel_hi:[1,1,0]
	v_and_b32_e32 v23, 0xffff0000, v4
	v_pk_mul_f32 v[26:27], v[26:27], v[32:33]
	v_lshlrev_b32_e32 v8, 16, v9
	v_pk_mul_f32 v[26:27], v[28:29], v[26:27]
	v_and_b32_e32 v9, 0xffff0000, v9
	v_pk_mul_f32 v[28:29], v[26:27], v[20:21]
	v_pk_fma_f32 v[20:21], v[26:27], v[20:21], v[20:21] neg_lo:[1,0,0] neg_hi:[1,0,0]
	v_lshlrev_b32_e32 v4, 16, v5
	v_cndmask_b32_e64 v21, v21, v29, s[0:1]
	v_cndmask_b32_e32 v20, v20, v28, vcc
	v_pk_mul_f32 v[20:21], v[20:21], v[22:23]
	v_pk_mul_f32 v[22:23], v[30:31], v[24:25]
	v_and_b32_e32 v5, 0xffff0000, v5
	v_pk_mul_f32 v[20:21], v[22:23], v[20:21]
	s_nop 0
	v_cvt_pk_bf16_f32 v0, v20, v21
	v_lshlrev_b32_e32 v20, 16, v1
	v_and_b32_e32 v21, 0xffff0000, v1
	v_fma_f32 v1, |v20|, s85, 1.0
	v_pk_mul_f32 v[24:25], v[20:21], v[20:21]
	v_rcp_f32_e32 v22, v1
	v_mul_f32_e32 v1, 0xbf38aa3b, v24
	v_exp_f32_e32 v24, v1
	v_mul_f32_e32 v1, 0xbfb8aa3b, v8
	v_exp_f32_e32 v1, v1
	v_cmp_gt_f32_e32 vcc, 0, v20
	v_cmp_gt_f32_e64 s[0:1], 0, v21
	v_add_f32_e32 v1, 1.0, v1
	v_rcp_f32_e32 v26, v1
	v_fma_f32 v1, |v21|, s85, 1.0
	v_rcp_f32_e32 v23, v1
	v_mul_f32_e32 v1, 0xbf38aa3b, v25
	v_exp_f32_e32 v25, v1
	v_mul_f32_e32 v1, 0xbfb8aa3b, v9
	v_exp_f32_e32 v1, v1
	v_pk_fma_f32 v[28:29], v[22:23], s[74:75], v[12:13] op_sel_hi:[1,0,0]
	v_add_f32_e32 v1, 1.0, v1
	v_pk_fma_f32 v[28:29], v[22:23], v[28:29], s[84:85] op_sel_hi:[1,1,0]
	v_rcp_f32_e32 v27, v1
	v_pk_fma_f32 v[28:29], v[22:23], v[28:29], s[86:87] op_sel_hi:[1,1,0]
	v_pk_mul_f32 v[8:9], v[26:27], v[8:9]
	v_pk_fma_f32 v[28:29], v[22:23], v[28:29], s[24:25] op_sel_hi:[1,1,0]
	s_nop 0
	v_pk_mul_f32 v[22:23], v[22:23], v[28:29]
	s_nop 0
	v_pk_mul_f32 v[22:23], v[24:25], v[22:23]
	s_nop 0
	v_pk_mul_f32 v[24:25], v[22:23], v[20:21]
	v_pk_fma_f32 v[20:21], v[22:23], v[20:21], v[20:21] neg_lo:[1,0,0] neg_hi:[1,0,0]
	s_nop 0
	v_cndmask_b32_e64 v21, v21, v25, s[0:1]
	v_cndmask_b32_e32 v20, v20, v24, vcc
	v_pk_mul_f32 v[4:5], v[20:21], v[4:5]
	v_lshlrev_b32_e32 v20, 16, v10
	v_pk_mul_f32 v[4:5], v[8:9], v[4:5]
	v_and_b32_e32 v21, 0xffff0000, v10
	v_cvt_pk_bf16_f32 v1, v4, v5
	v_lshlrev_b32_e32 v4, 16, v2
	v_and_b32_e32 v5, 0xffff0000, v2
	v_fma_f32 v2, |v4|, s85, 1.0
	v_pk_mul_f32 v[24:25], v[4:5], v[4:5]
	v_rcp_f32_e32 v22, v2
	v_mul_f32_e32 v2, 0xbf38aa3b, v24
	v_exp_f32_e32 v24, v2
	v_mul_f32_e32 v2, 0xbfb8aa3b, v20
	v_exp_f32_e32 v2, v2
	v_cmp_gt_f32_e32 vcc, 0, v4
	v_cmp_gt_f32_e64 s[0:1], 0, v5
	v_lshlrev_b32_e32 v8, 16, v6
	v_add_f32_e32 v2, 1.0, v2
	v_rcp_f32_e32 v26, v2
	v_fma_f32 v2, |v5|, s85, 1.0
	v_rcp_f32_e32 v23, v2
	v_mul_f32_e32 v2, 0xbf38aa3b, v25
	v_exp_f32_e32 v25, v2
	v_mul_f32_e32 v2, 0xbfb8aa3b, v21
	v_exp_f32_e32 v2, v2
	v_pk_fma_f32 v[28:29], v[22:23], s[74:75], v[12:13] op_sel_hi:[1,0,0]
	v_and_b32_e32 v9, 0xffff0000, v6
	v_pk_fma_f32 v[28:29], v[22:23], v[28:29], s[84:85] op_sel_hi:[1,1,0]
	v_add_f32_e32 v2, 1.0, v2
	v_pk_fma_f32 v[28:29], v[22:23], v[28:29], s[86:87] op_sel_hi:[1,1,0]
	v_rcp_f32_e32 v27, v2
	v_pk_fma_f32 v[28:29], v[22:23], v[28:29], s[24:25] op_sel_hi:[1,1,0]
	v_lshlrev_b32_e32 v6, 16, v7
	v_pk_mul_f32 v[22:23], v[22:23], v[28:29]
	v_and_b32_e32 v7, 0xffff0000, v7
	v_pk_mul_f32 v[22:23], v[24:25], v[22:23]
	s_nop 0
	v_pk_mul_f32 v[24:25], v[22:23], v[4:5]
	v_pk_fma_f32 v[4:5], v[22:23], v[4:5], v[4:5] neg_lo:[1,0,0] neg_hi:[1,0,0]
	s_nop 0
	v_cndmask_b32_e64 v5, v5, v25, s[0:1]
	v_cndmask_b32_e32 v4, v4, v24, vcc
	v_pk_mul_f32 v[4:5], v[4:5], v[8:9]
	v_pk_mul_f32 v[8:9], v[26:27], v[20:21]
	s_nop 0
	v_pk_mul_f32 v[4:5], v[8:9], v[4:5]
	v_lshlrev_b32_e32 v8, 16, v11
	v_cvt_pk_bf16_f32 v2, v4, v5
	v_lshlrev_b32_e32 v4, 16, v3
	v_and_b32_e32 v5, 0xffff0000, v3
	v_fma_f32 v3, |v4|, s85, 1.0
	v_pk_mul_f32 v[20:21], v[4:5], v[4:5]
	v_rcp_f32_e32 v10, v3
	v_mul_f32_e32 v3, 0xbf38aa3b, v20
	v_exp_f32_e32 v20, v3
	v_mul_f32_e32 v3, 0xbfb8aa3b, v8
	v_exp_f32_e32 v3, v3
	v_and_b32_e32 v9, 0xffff0000, v11
	v_cmp_gt_f32_e32 vcc, 0, v4
	v_cmp_gt_f32_e64 s[0:1], 0, v5
	v_add_f32_e32 v3, 1.0, v3
	v_rcp_f32_e32 v22, v3
	v_fma_f32 v3, |v5|, s85, 1.0
	v_rcp_f32_e32 v11, v3
	v_mul_f32_e32 v3, 0xbf38aa3b, v21
	v_exp_f32_e32 v21, v3
	v_mul_f32_e32 v3, 0xbfb8aa3b, v9
	v_exp_f32_e32 v3, v3
	v_pk_fma_f32 v[24:25], v[10:11], s[74:75], v[12:13] op_sel_hi:[1,0,0]
	v_add_f32_e32 v3, 1.0, v3
	v_pk_fma_f32 v[24:25], v[10:11], v[24:25], s[84:85] op_sel_hi:[1,1,0]
	v_rcp_f32_e32 v23, v3
	v_pk_fma_f32 v[24:25], v[10:11], v[24:25], s[86:87] op_sel_hi:[1,1,0]
	s_nop 0
	v_pk_fma_f32 v[24:25], v[10:11], v[24:25], s[24:25] op_sel_hi:[1,1,0]
	s_nop 0
	v_pk_mul_f32 v[10:11], v[10:11], v[24:25]
	s_nop 0
	v_pk_mul_f32 v[10:11], v[20:21], v[10:11]
	s_nop 0
	v_pk_mul_f32 v[20:21], v[10:11], v[4:5]
	v_pk_fma_f32 v[4:5], v[10:11], v[4:5], v[4:5] neg_lo:[1,0,0] neg_hi:[1,0,0]
	s_nop 0
	v_cndmask_b32_e64 v5, v5, v21, s[0:1]
	v_cndmask_b32_e32 v4, v4, v20, vcc
	v_pk_mul_f32 v[4:5], v[4:5], v[6:7]
	v_pk_mul_f32 v[6:7], v[22:23], v[8:9]
	s_mov_b32 s0, 0xc000
	v_pk_mul_f32 v[4:5], v[6:7], v[4:5]
	s_nop 0
	v_cvt_pk_bf16_f32 v3, v4, v5
	global_store_dwordx4 v[18:19], v[0:3], off offset:2048
	s_nop 1
	v_add_co_u32_e32 v0, vcc, s0, v14
	s_mov_b32 s0, 0xd000
	s_nop 0
	v_addc_co_u32_e32 v1, vcc, 0, v15, vcc
	v_add_co_u32_e32 v4, vcc, s0, v14
	s_mov_b32 s0, 0xb000
	s_nop 0
	v_addc_co_u32_e32 v5, vcc, 0, v15, vcc
	s_waitcnt vmcnt(15)
	v_mov_b64_e32 v[0:1], v[72:73]
	v_mov_b64_e32 v[2:3], v[74:75]
	v_add_co_u32_e32 v18, vcc, s0, v14
	v_mov_b64_e32 v[4:5], v[76:77]
	v_mov_b64_e32 v[6:7], v[78:79]
	s_nop 0
	v_addc_co_u32_e32 v19, vcc, 0, v15, vcc
	v_mov_b64_e32 v[8:9], v[80:81]
	v_mov_b64_e32 v[10:11], v[82:83]
	v_lshlrev_b32_e32 v20, 16, v0
	v_and_b32_e32 v21, 0xffff0000, v0
	v_fma_f32 v0, |v20|, s85, 1.0
	v_pk_mul_f32 v[28:29], v[20:21], v[20:21]
	v_rcp_f32_e32 v26, v0
	v_mul_f32_e32 v0, 0xbf38aa3b, v28
	v_lshlrev_b32_e32 v24, 16, v8
	v_exp_f32_e32 v28, v0
	v_mul_f32_e32 v0, 0xbfb8aa3b, v24
	v_exp_f32_e32 v0, v0
	v_and_b32_e32 v25, 0xffff0000, v8
	v_cmp_gt_f32_e32 vcc, 0, v20
	v_cmp_gt_f32_e64 s[0:1], 0, v21
	v_add_f32_e32 v0, 1.0, v0
	v_rcp_f32_e32 v30, v0
	v_fma_f32 v0, |v21|, s85, 1.0
	v_rcp_f32_e32 v27, v0
	v_mul_f32_e32 v0, 0xbf38aa3b, v29
	v_exp_f32_e32 v29, v0
	v_mul_f32_e32 v0, 0xbfb8aa3b, v25
	v_exp_f32_e32 v0, v0
	v_pk_fma_f32 v[32:33], v[26:27], s[74:75], v[12:13] op_sel_hi:[1,0,0]
	v_lshlrev_b32_e32 v22, 16, v4
	v_pk_fma_f32 v[32:33], v[26:27], v[32:33], s[84:85] op_sel_hi:[1,1,0]
	v_add_f32_e32 v0, 1.0, v0
	v_pk_fma_f32 v[32:33], v[26:27], v[32:33], s[86:87] op_sel_hi:[1,1,0]
	v_rcp_f32_e32 v31, v0
	v_pk_fma_f32 v[32:33], v[26:27], v[32:33], s[24:25] op_sel_hi:[1,1,0]
	v_and_b32_e32 v23, 0xffff0000, v4
	v_pk_mul_f32 v[26:27], v[26:27], v[32:33]
	v_lshlrev_b32_e32 v8, 16, v9
	v_pk_mul_f32 v[26:27], v[28:29], v[26:27]
	v_and_b32_e32 v9, 0xffff0000, v9
	v_pk_mul_f32 v[28:29], v[26:27], v[20:21]
	v_pk_fma_f32 v[20:21], v[26:27], v[20:21], v[20:21] neg_lo:[1,0,0] neg_hi:[1,0,0]
	v_lshlrev_b32_e32 v4, 16, v5
	v_cndmask_b32_e64 v21, v21, v29, s[0:1]
	v_cndmask_b32_e32 v20, v20, v28, vcc
	v_pk_mul_f32 v[20:21], v[20:21], v[22:23]
	v_pk_mul_f32 v[22:23], v[30:31], v[24:25]
	v_and_b32_e32 v5, 0xffff0000, v5
	v_pk_mul_f32 v[20:21], v[22:23], v[20:21]
	s_nop 0
	v_cvt_pk_bf16_f32 v0, v20, v21
	v_lshlrev_b32_e32 v20, 16, v1
	v_and_b32_e32 v21, 0xffff0000, v1
	v_fma_f32 v1, |v20|, s85, 1.0
	v_pk_mul_f32 v[24:25], v[20:21], v[20:21]
	v_rcp_f32_e32 v22, v1
	v_mul_f32_e32 v1, 0xbf38aa3b, v24
	v_exp_f32_e32 v24, v1
	v_mul_f32_e32 v1, 0xbfb8aa3b, v8
	v_exp_f32_e32 v1, v1
	v_cmp_gt_f32_e32 vcc, 0, v20
	v_cmp_gt_f32_e64 s[0:1], 0, v21
	v_add_f32_e32 v1, 1.0, v1
	v_rcp_f32_e32 v26, v1
	v_fma_f32 v1, |v21|, s85, 1.0
	v_rcp_f32_e32 v23, v1
	v_mul_f32_e32 v1, 0xbf38aa3b, v25
	v_exp_f32_e32 v25, v1
	v_mul_f32_e32 v1, 0xbfb8aa3b, v9
	v_exp_f32_e32 v1, v1
	v_pk_fma_f32 v[28:29], v[22:23], s[74:75], v[12:13] op_sel_hi:[1,0,0]
	v_add_f32_e32 v1, 1.0, v1
	v_pk_fma_f32 v[28:29], v[22:23], v[28:29], s[84:85] op_sel_hi:[1,1,0]
	v_rcp_f32_e32 v27, v1
	v_pk_fma_f32 v[28:29], v[22:23], v[28:29], s[86:87] op_sel_hi:[1,1,0]
	v_pk_mul_f32 v[8:9], v[26:27], v[8:9]
	v_pk_fma_f32 v[28:29], v[22:23], v[28:29], s[24:25] op_sel_hi:[1,1,0]
	s_nop 0
	v_pk_mul_f32 v[22:23], v[22:23], v[28:29]
	s_nop 0
	v_pk_mul_f32 v[22:23], v[24:25], v[22:23]
	s_nop 0
	v_pk_mul_f32 v[24:25], v[22:23], v[20:21]
	v_pk_fma_f32 v[20:21], v[22:23], v[20:21], v[20:21] neg_lo:[1,0,0] neg_hi:[1,0,0]
	s_nop 0
	v_cndmask_b32_e64 v21, v21, v25, s[0:1]
	v_cndmask_b32_e32 v20, v20, v24, vcc
	v_pk_mul_f32 v[4:5], v[20:21], v[4:5]
	v_lshlrev_b32_e32 v20, 16, v10
	v_pk_mul_f32 v[4:5], v[8:9], v[4:5]
	v_and_b32_e32 v21, 0xffff0000, v10
	v_cvt_pk_bf16_f32 v1, v4, v5
	v_lshlrev_b32_e32 v4, 16, v2
	v_and_b32_e32 v5, 0xffff0000, v2
	v_fma_f32 v2, |v4|, s85, 1.0
	v_pk_mul_f32 v[24:25], v[4:5], v[4:5]
	v_rcp_f32_e32 v22, v2
	v_mul_f32_e32 v2, 0xbf38aa3b, v24
	v_exp_f32_e32 v24, v2
	v_mul_f32_e32 v2, 0xbfb8aa3b, v20
	v_exp_f32_e32 v2, v2
	v_cmp_gt_f32_e32 vcc, 0, v4
	v_cmp_gt_f32_e64 s[0:1], 0, v5
	v_lshlrev_b32_e32 v8, 16, v6
	v_add_f32_e32 v2, 1.0, v2
	v_rcp_f32_e32 v26, v2
	v_fma_f32 v2, |v5|, s85, 1.0
	v_rcp_f32_e32 v23, v2
	v_mul_f32_e32 v2, 0xbf38aa3b, v25
	v_exp_f32_e32 v25, v2
	v_mul_f32_e32 v2, 0xbfb8aa3b, v21
	v_exp_f32_e32 v2, v2
	v_pk_fma_f32 v[28:29], v[22:23], s[74:75], v[12:13] op_sel_hi:[1,0,0]
	v_and_b32_e32 v9, 0xffff0000, v6
	v_pk_fma_f32 v[28:29], v[22:23], v[28:29], s[84:85] op_sel_hi:[1,1,0]
	v_add_f32_e32 v2, 1.0, v2
	v_pk_fma_f32 v[28:29], v[22:23], v[28:29], s[86:87] op_sel_hi:[1,1,0]
	v_rcp_f32_e32 v27, v2
	v_pk_fma_f32 v[28:29], v[22:23], v[28:29], s[24:25] op_sel_hi:[1,1,0]
	v_lshlrev_b32_e32 v6, 16, v7
	v_pk_mul_f32 v[22:23], v[22:23], v[28:29]
	v_and_b32_e32 v7, 0xffff0000, v7
	v_pk_mul_f32 v[22:23], v[24:25], v[22:23]
	s_nop 0
	v_pk_mul_f32 v[24:25], v[22:23], v[4:5]
	v_pk_fma_f32 v[4:5], v[22:23], v[4:5], v[4:5] neg_lo:[1,0,0] neg_hi:[1,0,0]
	s_nop 0
	v_cndmask_b32_e64 v5, v5, v25, s[0:1]
	v_cndmask_b32_e32 v4, v4, v24, vcc
	v_pk_mul_f32 v[4:5], v[4:5], v[8:9]
	v_pk_mul_f32 v[8:9], v[26:27], v[20:21]
	s_nop 0
	v_pk_mul_f32 v[4:5], v[8:9], v[4:5]
	v_lshlrev_b32_e32 v8, 16, v11
	v_cvt_pk_bf16_f32 v2, v4, v5
	v_lshlrev_b32_e32 v4, 16, v3
	v_and_b32_e32 v5, 0xffff0000, v3
	v_fma_f32 v3, |v4|, s85, 1.0
	v_pk_mul_f32 v[20:21], v[4:5], v[4:5]
	v_rcp_f32_e32 v10, v3
	v_mul_f32_e32 v3, 0xbf38aa3b, v20
	v_exp_f32_e32 v20, v3
	v_mul_f32_e32 v3, 0xbfb8aa3b, v8
	v_exp_f32_e32 v3, v3
	v_and_b32_e32 v9, 0xffff0000, v11
	v_cmp_gt_f32_e32 vcc, 0, v4
	v_cmp_gt_f32_e64 s[0:1], 0, v5
	v_add_f32_e32 v3, 1.0, v3
	v_rcp_f32_e32 v22, v3
	v_fma_f32 v3, |v5|, s85, 1.0
	v_rcp_f32_e32 v11, v3
	v_mul_f32_e32 v3, 0xbf38aa3b, v21
	v_exp_f32_e32 v21, v3
	v_mul_f32_e32 v3, 0xbfb8aa3b, v9
	v_exp_f32_e32 v3, v3
	v_pk_fma_f32 v[24:25], v[10:11], s[74:75], v[12:13] op_sel_hi:[1,0,0]
	v_add_f32_e32 v3, 1.0, v3
	v_pk_fma_f32 v[24:25], v[10:11], v[24:25], s[84:85] op_sel_hi:[1,1,0]
	v_rcp_f32_e32 v23, v3
	v_pk_fma_f32 v[24:25], v[10:11], v[24:25], s[86:87] op_sel_hi:[1,1,0]
	s_nop 0
	v_pk_fma_f32 v[24:25], v[10:11], v[24:25], s[24:25] op_sel_hi:[1,1,0]
	s_nop 0
	v_pk_mul_f32 v[10:11], v[10:11], v[24:25]
	s_nop 0
	v_pk_mul_f32 v[10:11], v[20:21], v[10:11]
	s_nop 0
	v_pk_mul_f32 v[20:21], v[10:11], v[4:5]
	v_pk_fma_f32 v[4:5], v[10:11], v[4:5], v[4:5] neg_lo:[1,0,0] neg_hi:[1,0,0]
	s_nop 0
	v_cndmask_b32_e64 v5, v5, v21, s[0:1]
	v_cndmask_b32_e32 v4, v4, v20, vcc
	v_pk_mul_f32 v[4:5], v[4:5], v[6:7]
	v_pk_mul_f32 v[6:7], v[22:23], v[8:9]
	s_mov_b32 s0, 0x10000
	v_pk_mul_f32 v[4:5], v[6:7], v[4:5]
	s_nop 0
	v_cvt_pk_bf16_f32 v3, v4, v5
	v_add_co_u32_e32 v4, vcc, s0, v14
	global_store_dwordx4 v[18:19], v[0:3], off
	s_nop 0
	v_addc_co_u32_e32 v5, vcc, 0, v15, vcc
	v_add_co_u32_e32 v18, vcc, s56, v14
	s_waitcnt vmcnt(13)
	v_mov_b64_e32 v[0:1], v[84:85]
	v_mov_b64_e32 v[2:3], v[86:87]
	s_nop 0
	v_mov_b64_e32 v[4:5], v[88:89]
	v_mov_b64_e32 v[6:7], v[90:91]
	v_addc_co_u32_e32 v19, vcc, 0, v15, vcc
	v_mov_b64_e32 v[8:9], v[92:93]
	v_mov_b64_e32 v[10:11], v[94:95]
	v_lshlrev_b32_e32 v20, 16, v0
	v_and_b32_e32 v21, 0xffff0000, v0
	v_fma_f32 v0, |v20|, s85, 1.0
	v_pk_mul_f32 v[28:29], v[20:21], v[20:21]
	v_lshlrev_b32_e32 v24, 16, v8
	v_rcp_f32_e32 v26, v0
	v_mul_f32_e32 v0, 0xbf38aa3b, v28
	v_exp_f32_e32 v28, v0
	v_mul_f32_e32 v0, 0xbfb8aa3b, v24
	v_exp_f32_e32 v0, v0
	v_and_b32_e32 v25, 0xffff0000, v8
	v_cmp_gt_f32_e32 vcc, 0, v20
	v_cmp_gt_f32_e64 s[0:1], 0, v21
	v_add_f32_e32 v0, 1.0, v0
	v_rcp_f32_e32 v30, v0
	v_fma_f32 v0, |v21|, s85, 1.0
	v_rcp_f32_e32 v27, v0
	v_mul_f32_e32 v0, 0xbf38aa3b, v29
	v_exp_f32_e32 v29, v0
	v_mul_f32_e32 v0, 0xbfb8aa3b, v25
	v_exp_f32_e32 v0, v0
	v_pk_fma_f32 v[32:33], v[26:27], s[74:75], v[12:13] op_sel_hi:[1,0,0]
	v_lshlrev_b32_e32 v22, 16, v4
	v_pk_fma_f32 v[32:33], v[26:27], v[32:33], s[84:85] op_sel_hi:[1,1,0]
	v_add_f32_e32 v0, 1.0, v0
	v_pk_fma_f32 v[32:33], v[26:27], v[32:33], s[86:87] op_sel_hi:[1,1,0]
	v_rcp_f32_e32 v31, v0
	v_pk_fma_f32 v[32:33], v[26:27], v[32:33], s[24:25] op_sel_hi:[1,1,0]
	v_and_b32_e32 v23, 0xffff0000, v4
	v_pk_mul_f32 v[26:27], v[26:27], v[32:33]
	v_lshlrev_b32_e32 v8, 16, v9
	v_pk_mul_f32 v[26:27], v[28:29], v[26:27]
	v_and_b32_e32 v9, 0xffff0000, v9
	v_pk_mul_f32 v[28:29], v[26:27], v[20:21]
	v_pk_fma_f32 v[20:21], v[26:27], v[20:21], v[20:21] neg_lo:[1,0,0] neg_hi:[1,0,0]
	v_lshlrev_b32_e32 v4, 16, v5
	v_cndmask_b32_e64 v21, v21, v29, s[0:1]
	v_cndmask_b32_e32 v20, v20, v28, vcc
	v_pk_mul_f32 v[20:21], v[20:21], v[22:23]
	v_pk_mul_f32 v[22:23], v[30:31], v[24:25]
	v_and_b32_e32 v5, 0xffff0000, v5
	v_pk_mul_f32 v[20:21], v[22:23], v[20:21]
	s_nop 0
	v_cvt_pk_bf16_f32 v0, v20, v21
	v_lshlrev_b32_e32 v20, 16, v1
	v_and_b32_e32 v21, 0xffff0000, v1
	v_fma_f32 v1, |v20|, s85, 1.0
	v_pk_mul_f32 v[24:25], v[20:21], v[20:21]
	v_rcp_f32_e32 v22, v1
	v_mul_f32_e32 v1, 0xbf38aa3b, v24
	v_exp_f32_e32 v24, v1
	v_mul_f32_e32 v1, 0xbfb8aa3b, v8
	v_exp_f32_e32 v1, v1
	v_cmp_gt_f32_e32 vcc, 0, v20
	v_cmp_gt_f32_e64 s[0:1], 0, v21
	v_add_f32_e32 v1, 1.0, v1
	v_rcp_f32_e32 v26, v1
	v_fma_f32 v1, |v21|, s85, 1.0
	v_rcp_f32_e32 v23, v1
	v_mul_f32_e32 v1, 0xbf38aa3b, v25
	v_exp_f32_e32 v25, v1
	v_mul_f32_e32 v1, 0xbfb8aa3b, v9
	v_exp_f32_e32 v1, v1
	v_pk_fma_f32 v[28:29], v[22:23], s[74:75], v[12:13] op_sel_hi:[1,0,0]
	v_add_f32_e32 v1, 1.0, v1
	v_pk_fma_f32 v[28:29], v[22:23], v[28:29], s[84:85] op_sel_hi:[1,1,0]
	v_rcp_f32_e32 v27, v1
	v_pk_fma_f32 v[28:29], v[22:23], v[28:29], s[86:87] op_sel_hi:[1,1,0]
	v_pk_mul_f32 v[8:9], v[26:27], v[8:9]
	v_pk_fma_f32 v[28:29], v[22:23], v[28:29], s[24:25] op_sel_hi:[1,1,0]
	s_nop 0
	v_pk_mul_f32 v[22:23], v[22:23], v[28:29]
	s_nop 0
	v_pk_mul_f32 v[22:23], v[24:25], v[22:23]
	s_nop 0
	v_pk_mul_f32 v[24:25], v[22:23], v[20:21]
	v_pk_fma_f32 v[20:21], v[22:23], v[20:21], v[20:21] neg_lo:[1,0,0] neg_hi:[1,0,0]
	s_nop 0
	v_cndmask_b32_e64 v21, v21, v25, s[0:1]
	v_cndmask_b32_e32 v20, v20, v24, vcc
	v_pk_mul_f32 v[4:5], v[20:21], v[4:5]
	v_lshlrev_b32_e32 v20, 16, v10
	v_pk_mul_f32 v[4:5], v[8:9], v[4:5]
	v_and_b32_e32 v21, 0xffff0000, v10
	v_cvt_pk_bf16_f32 v1, v4, v5
	v_lshlrev_b32_e32 v4, 16, v2
	v_and_b32_e32 v5, 0xffff0000, v2
	v_fma_f32 v2, |v4|, s85, 1.0
	v_pk_mul_f32 v[24:25], v[4:5], v[4:5]
	v_rcp_f32_e32 v22, v2
	v_mul_f32_e32 v2, 0xbf38aa3b, v24
	v_exp_f32_e32 v24, v2
	v_mul_f32_e32 v2, 0xbfb8aa3b, v20
	v_exp_f32_e32 v2, v2
	v_cmp_gt_f32_e32 vcc, 0, v4
	v_cmp_gt_f32_e64 s[0:1], 0, v5
	v_lshlrev_b32_e32 v8, 16, v6
	v_add_f32_e32 v2, 1.0, v2
	v_rcp_f32_e32 v26, v2
	v_fma_f32 v2, |v5|, s85, 1.0
	v_rcp_f32_e32 v23, v2
	v_mul_f32_e32 v2, 0xbf38aa3b, v25
	v_exp_f32_e32 v25, v2
	v_mul_f32_e32 v2, 0xbfb8aa3b, v21
	v_exp_f32_e32 v2, v2
	v_pk_fma_f32 v[28:29], v[22:23], s[74:75], v[12:13] op_sel_hi:[1,0,0]
	v_and_b32_e32 v9, 0xffff0000, v6
	v_pk_fma_f32 v[28:29], v[22:23], v[28:29], s[84:85] op_sel_hi:[1,1,0]
	v_add_f32_e32 v2, 1.0, v2
	v_pk_fma_f32 v[28:29], v[22:23], v[28:29], s[86:87] op_sel_hi:[1,1,0]
	v_rcp_f32_e32 v27, v2
	v_pk_fma_f32 v[28:29], v[22:23], v[28:29], s[24:25] op_sel_hi:[1,1,0]
	v_lshlrev_b32_e32 v6, 16, v7
	v_pk_mul_f32 v[22:23], v[22:23], v[28:29]
	v_and_b32_e32 v7, 0xffff0000, v7
	v_pk_mul_f32 v[22:23], v[24:25], v[22:23]
	s_nop 0
	v_pk_mul_f32 v[24:25], v[22:23], v[4:5]
	v_pk_fma_f32 v[4:5], v[22:23], v[4:5], v[4:5] neg_lo:[1,0,0] neg_hi:[1,0,0]
	s_nop 0
	v_cndmask_b32_e64 v5, v5, v25, s[0:1]
	v_cndmask_b32_e32 v4, v4, v24, vcc
	v_pk_mul_f32 v[4:5], v[4:5], v[8:9]
	v_pk_mul_f32 v[8:9], v[26:27], v[20:21]
	s_nop 0
	v_pk_mul_f32 v[4:5], v[8:9], v[4:5]
	v_lshlrev_b32_e32 v8, 16, v11
	v_cvt_pk_bf16_f32 v2, v4, v5
	v_lshlrev_b32_e32 v4, 16, v3
	v_and_b32_e32 v5, 0xffff0000, v3
	v_fma_f32 v3, |v4|, s85, 1.0
	v_pk_mul_f32 v[20:21], v[4:5], v[4:5]
	v_rcp_f32_e32 v10, v3
	v_mul_f32_e32 v3, 0xbf38aa3b, v20
	v_exp_f32_e32 v20, v3
	v_mul_f32_e32 v3, 0xbfb8aa3b, v8
	v_exp_f32_e32 v3, v3
	v_and_b32_e32 v9, 0xffff0000, v11
	v_cmp_gt_f32_e32 vcc, 0, v4
	v_cmp_gt_f32_e64 s[0:1], 0, v5
	v_add_f32_e32 v3, 1.0, v3
	v_rcp_f32_e32 v22, v3
	v_fma_f32 v3, |v5|, s85, 1.0
	v_rcp_f32_e32 v11, v3
	v_mul_f32_e32 v3, 0xbf38aa3b, v21
	v_exp_f32_e32 v21, v3
	v_mul_f32_e32 v3, 0xbfb8aa3b, v9
	v_exp_f32_e32 v3, v3
	v_pk_fma_f32 v[24:25], v[10:11], s[74:75], v[12:13] op_sel_hi:[1,0,0]
	v_add_f32_e32 v3, 1.0, v3
	v_pk_fma_f32 v[24:25], v[10:11], v[24:25], s[84:85] op_sel_hi:[1,1,0]
	v_rcp_f32_e32 v23, v3
	v_pk_fma_f32 v[24:25], v[10:11], v[24:25], s[86:87] op_sel_hi:[1,1,0]
	s_nop 0
	v_pk_fma_f32 v[24:25], v[10:11], v[24:25], s[24:25] op_sel_hi:[1,1,0]
	s_nop 0
	v_pk_mul_f32 v[10:11], v[10:11], v[24:25]
	s_nop 0
	v_pk_mul_f32 v[10:11], v[20:21], v[10:11]
	s_nop 0
	v_pk_mul_f32 v[20:21], v[10:11], v[4:5]
	v_pk_fma_f32 v[4:5], v[10:11], v[4:5], v[4:5] neg_lo:[1,0,0] neg_hi:[1,0,0]
	s_nop 0
	v_cndmask_b32_e64 v5, v5, v21, s[0:1]
	v_cndmask_b32_e32 v4, v4, v20, vcc
	v_pk_mul_f32 v[4:5], v[4:5], v[6:7]
	v_pk_mul_f32 v[6:7], v[22:23], v[8:9]
	s_mov_b32 s0, 0x13000
	v_pk_mul_f32 v[4:5], v[6:7], v[4:5]
	s_nop 0
	v_cvt_pk_bf16_f32 v3, v4, v5
	global_store_dwordx4 v[18:19], v[0:3], off offset:2048
	s_nop 1
	v_add_co_u32_e32 v0, vcc, s0, v14
	s_mov_b32 s0, 0x14000
	s_nop 0
	v_addc_co_u32_e32 v1, vcc, 0, v15, vcc
	v_add_co_u32_e32 v4, vcc, s0, v14
	s_mov_b32 s0, 0x12000
	s_nop 0
	v_addc_co_u32_e32 v5, vcc, 0, v15, vcc
	s_waitcnt vmcnt(11)
	v_mov_b64_e32 v[0:1], v[96:97]
	v_mov_b64_e32 v[2:3], v[98:99]
	v_add_co_u32_e32 v18, vcc, s0, v14
	v_mov_b64_e32 v[4:5], v[100:101]
	v_mov_b64_e32 v[6:7], v[102:103]
	s_nop 0
	v_addc_co_u32_e32 v19, vcc, 0, v15, vcc
	v_mov_b64_e32 v[8:9], v[104:105]
	v_mov_b64_e32 v[10:11], v[106:107]
	v_lshlrev_b32_e32 v20, 16, v0
	v_and_b32_e32 v21, 0xffff0000, v0
	v_fma_f32 v0, |v20|, s85, 1.0
	v_pk_mul_f32 v[28:29], v[20:21], v[20:21]
	v_rcp_f32_e32 v26, v0
	v_mul_f32_e32 v0, 0xbf38aa3b, v28
	v_lshlrev_b32_e32 v24, 16, v8
	v_exp_f32_e32 v28, v0
	v_mul_f32_e32 v0, 0xbfb8aa3b, v24
	v_exp_f32_e32 v0, v0
	v_and_b32_e32 v25, 0xffff0000, v8
	v_cmp_gt_f32_e32 vcc, 0, v20
	v_cmp_gt_f32_e64 s[0:1], 0, v21
	v_add_f32_e32 v0, 1.0, v0
	v_rcp_f32_e32 v30, v0
	v_fma_f32 v0, |v21|, s85, 1.0
	v_rcp_f32_e32 v27, v0
	v_mul_f32_e32 v0, 0xbf38aa3b, v29
	v_exp_f32_e32 v29, v0
	v_mul_f32_e32 v0, 0xbfb8aa3b, v25
	v_exp_f32_e32 v0, v0
	v_pk_fma_f32 v[32:33], v[26:27], s[74:75], v[12:13] op_sel_hi:[1,0,0]
	v_lshlrev_b32_e32 v22, 16, v4
	v_pk_fma_f32 v[32:33], v[26:27], v[32:33], s[84:85] op_sel_hi:[1,1,0]
	v_add_f32_e32 v0, 1.0, v0
	v_pk_fma_f32 v[32:33], v[26:27], v[32:33], s[86:87] op_sel_hi:[1,1,0]
	v_rcp_f32_e32 v31, v0
	v_pk_fma_f32 v[32:33], v[26:27], v[32:33], s[24:25] op_sel_hi:[1,1,0]
	v_and_b32_e32 v23, 0xffff0000, v4
	v_pk_mul_f32 v[26:27], v[26:27], v[32:33]
	v_lshlrev_b32_e32 v8, 16, v9
	v_pk_mul_f32 v[26:27], v[28:29], v[26:27]
	v_and_b32_e32 v9, 0xffff0000, v9
	v_pk_mul_f32 v[28:29], v[26:27], v[20:21]
	v_pk_fma_f32 v[20:21], v[26:27], v[20:21], v[20:21] neg_lo:[1,0,0] neg_hi:[1,0,0]
	v_lshlrev_b32_e32 v4, 16, v5
	v_cndmask_b32_e64 v21, v21, v29, s[0:1]
	v_cndmask_b32_e32 v20, v20, v28, vcc
	v_pk_mul_f32 v[20:21], v[20:21], v[22:23]
	v_pk_mul_f32 v[22:23], v[30:31], v[24:25]
	v_and_b32_e32 v5, 0xffff0000, v5
	v_pk_mul_f32 v[20:21], v[22:23], v[20:21]
	s_nop 0
	v_cvt_pk_bf16_f32 v0, v20, v21
	v_lshlrev_b32_e32 v20, 16, v1
	v_and_b32_e32 v21, 0xffff0000, v1
	v_fma_f32 v1, |v20|, s85, 1.0
	v_pk_mul_f32 v[24:25], v[20:21], v[20:21]
	v_rcp_f32_e32 v22, v1
	v_mul_f32_e32 v1, 0xbf38aa3b, v24
	v_exp_f32_e32 v24, v1
	v_mul_f32_e32 v1, 0xbfb8aa3b, v8
	v_exp_f32_e32 v1, v1
	v_cmp_gt_f32_e32 vcc, 0, v20
	v_cmp_gt_f32_e64 s[0:1], 0, v21
	v_add_f32_e32 v1, 1.0, v1
	v_rcp_f32_e32 v26, v1
	v_fma_f32 v1, |v21|, s85, 1.0
	v_rcp_f32_e32 v23, v1
	v_mul_f32_e32 v1, 0xbf38aa3b, v25
	v_exp_f32_e32 v25, v1
	v_mul_f32_e32 v1, 0xbfb8aa3b, v9
	v_exp_f32_e32 v1, v1
	v_pk_fma_f32 v[28:29], v[22:23], s[74:75], v[12:13] op_sel_hi:[1,0,0]
	v_add_f32_e32 v1, 1.0, v1
	v_pk_fma_f32 v[28:29], v[22:23], v[28:29], s[84:85] op_sel_hi:[1,1,0]
	v_rcp_f32_e32 v27, v1
	v_pk_fma_f32 v[28:29], v[22:23], v[28:29], s[86:87] op_sel_hi:[1,1,0]
	v_pk_mul_f32 v[8:9], v[26:27], v[8:9]
	v_pk_fma_f32 v[28:29], v[22:23], v[28:29], s[24:25] op_sel_hi:[1,1,0]
	s_nop 0
	v_pk_mul_f32 v[22:23], v[22:23], v[28:29]
	s_nop 0
	v_pk_mul_f32 v[22:23], v[24:25], v[22:23]
	s_nop 0
	v_pk_mul_f32 v[24:25], v[22:23], v[20:21]
	v_pk_fma_f32 v[20:21], v[22:23], v[20:21], v[20:21] neg_lo:[1,0,0] neg_hi:[1,0,0]
	s_nop 0
	v_cndmask_b32_e64 v21, v21, v25, s[0:1]
	v_cndmask_b32_e32 v20, v20, v24, vcc
	v_pk_mul_f32 v[4:5], v[20:21], v[4:5]
	v_lshlrev_b32_e32 v20, 16, v10
	v_pk_mul_f32 v[4:5], v[8:9], v[4:5]
	v_and_b32_e32 v21, 0xffff0000, v10
	v_cvt_pk_bf16_f32 v1, v4, v5
	v_lshlrev_b32_e32 v4, 16, v2
	v_and_b32_e32 v5, 0xffff0000, v2
	v_fma_f32 v2, |v4|, s85, 1.0
	v_pk_mul_f32 v[24:25], v[4:5], v[4:5]
	v_rcp_f32_e32 v22, v2
	v_mul_f32_e32 v2, 0xbf38aa3b, v24
	v_exp_f32_e32 v24, v2
	v_mul_f32_e32 v2, 0xbfb8aa3b, v20
	v_exp_f32_e32 v2, v2
	v_cmp_gt_f32_e32 vcc, 0, v4
	v_cmp_gt_f32_e64 s[0:1], 0, v5
	v_lshlrev_b32_e32 v8, 16, v6
	v_add_f32_e32 v2, 1.0, v2
	v_rcp_f32_e32 v26, v2
	v_fma_f32 v2, |v5|, s85, 1.0
	v_rcp_f32_e32 v23, v2
	v_mul_f32_e32 v2, 0xbf38aa3b, v25
	v_exp_f32_e32 v25, v2
	v_mul_f32_e32 v2, 0xbfb8aa3b, v21
	v_exp_f32_e32 v2, v2
	v_pk_fma_f32 v[28:29], v[22:23], s[74:75], v[12:13] op_sel_hi:[1,0,0]
	v_and_b32_e32 v9, 0xffff0000, v6
	v_pk_fma_f32 v[28:29], v[22:23], v[28:29], s[84:85] op_sel_hi:[1,1,0]
	v_add_f32_e32 v2, 1.0, v2
	v_pk_fma_f32 v[28:29], v[22:23], v[28:29], s[86:87] op_sel_hi:[1,1,0]
	v_rcp_f32_e32 v27, v2
	v_pk_fma_f32 v[28:29], v[22:23], v[28:29], s[24:25] op_sel_hi:[1,1,0]
	v_lshlrev_b32_e32 v6, 16, v7
	v_pk_mul_f32 v[22:23], v[22:23], v[28:29]
	v_and_b32_e32 v7, 0xffff0000, v7
	v_pk_mul_f32 v[22:23], v[24:25], v[22:23]
	s_nop 0
	v_pk_mul_f32 v[24:25], v[22:23], v[4:5]
	v_pk_fma_f32 v[4:5], v[22:23], v[4:5], v[4:5] neg_lo:[1,0,0] neg_hi:[1,0,0]
	s_nop 0
	v_cndmask_b32_e64 v5, v5, v25, s[0:1]
	v_cndmask_b32_e32 v4, v4, v24, vcc
	v_pk_mul_f32 v[4:5], v[4:5], v[8:9]
	v_pk_mul_f32 v[8:9], v[26:27], v[20:21]
	s_nop 0
	v_pk_mul_f32 v[4:5], v[8:9], v[4:5]
	v_lshlrev_b32_e32 v8, 16, v11
	v_cvt_pk_bf16_f32 v2, v4, v5
	v_lshlrev_b32_e32 v4, 16, v3
	v_and_b32_e32 v5, 0xffff0000, v3
	v_fma_f32 v3, |v4|, s85, 1.0
	v_pk_mul_f32 v[20:21], v[4:5], v[4:5]
	v_rcp_f32_e32 v10, v3
	v_mul_f32_e32 v3, 0xbf38aa3b, v20
	v_exp_f32_e32 v20, v3
	v_mul_f32_e32 v3, 0xbfb8aa3b, v8
	v_exp_f32_e32 v3, v3
	v_and_b32_e32 v9, 0xffff0000, v11
	v_cmp_gt_f32_e32 vcc, 0, v4
	v_cmp_gt_f32_e64 s[0:1], 0, v5
	v_add_f32_e32 v3, 1.0, v3
	v_rcp_f32_e32 v22, v3
	v_fma_f32 v3, |v5|, s85, 1.0
	v_rcp_f32_e32 v11, v3
	v_mul_f32_e32 v3, 0xbf38aa3b, v21
	v_exp_f32_e32 v21, v3
	v_mul_f32_e32 v3, 0xbfb8aa3b, v9
	v_exp_f32_e32 v3, v3
	v_pk_fma_f32 v[24:25], v[10:11], s[74:75], v[12:13] op_sel_hi:[1,0,0]
	v_add_f32_e32 v3, 1.0, v3
	v_pk_fma_f32 v[24:25], v[10:11], v[24:25], s[84:85] op_sel_hi:[1,1,0]
	v_rcp_f32_e32 v23, v3
	v_pk_fma_f32 v[24:25], v[10:11], v[24:25], s[86:87] op_sel_hi:[1,1,0]
	s_nop 0
	v_pk_fma_f32 v[24:25], v[10:11], v[24:25], s[24:25] op_sel_hi:[1,1,0]
	s_nop 0
	v_pk_mul_f32 v[10:11], v[10:11], v[24:25]
	s_nop 0
	v_pk_mul_f32 v[10:11], v[20:21], v[10:11]
	s_nop 0
	v_pk_mul_f32 v[20:21], v[10:11], v[4:5]
	v_pk_fma_f32 v[4:5], v[10:11], v[4:5], v[4:5] neg_lo:[1,0,0] neg_hi:[1,0,0]
	s_nop 0
	v_cndmask_b32_e64 v5, v5, v21, s[0:1]
	v_cndmask_b32_e32 v4, v4, v20, vcc
	v_pk_mul_f32 v[4:5], v[4:5], v[6:7]
	v_pk_mul_f32 v[6:7], v[22:23], v[8:9]
	s_nop 0
	v_pk_mul_f32 v[4:5], v[6:7], v[4:5]
	s_nop 0
	v_cvt_pk_bf16_f32 v3, v4, v5
	v_add_co_u32_e32 v4, vcc, s33, v14
	global_store_dwordx4 v[18:19], v[0:3], off
	s_nop 0
	v_addc_co_u32_e32 v5, vcc, 0, v15, vcc
	v_add_co_u32_e32 v18, vcc, s34, v14
	s_waitcnt vmcnt(9)
	v_mov_b64_e32 v[0:1], v[108:109]
	v_mov_b64_e32 v[2:3], v[110:111]
	s_nop 0
	v_mov_b64_e32 v[4:5], v[112:113]
	v_mov_b64_e32 v[6:7], v[114:115]
	v_addc_co_u32_e32 v19, vcc, 0, v15, vcc
	v_mov_b64_e32 v[8:9], v[116:117]
	v_mov_b64_e32 v[10:11], v[118:119]
	v_lshlrev_b32_e32 v20, 16, v0
	v_and_b32_e32 v21, 0xffff0000, v0
	v_fma_f32 v0, |v20|, s85, 1.0
	v_pk_mul_f32 v[28:29], v[20:21], v[20:21]
	v_lshlrev_b32_e32 v24, 16, v8
	v_rcp_f32_e32 v26, v0
	v_mul_f32_e32 v0, 0xbf38aa3b, v28
	v_exp_f32_e32 v28, v0
	v_mul_f32_e32 v0, 0xbfb8aa3b, v24
	v_exp_f32_e32 v0, v0
	v_and_b32_e32 v25, 0xffff0000, v8
	v_cmp_gt_f32_e32 vcc, 0, v20
	v_cmp_gt_f32_e64 s[0:1], 0, v21
	v_add_f32_e32 v0, 1.0, v0
	v_rcp_f32_e32 v30, v0
	v_fma_f32 v0, |v21|, s85, 1.0
	v_rcp_f32_e32 v27, v0
	v_mul_f32_e32 v0, 0xbf38aa3b, v29
	v_exp_f32_e32 v29, v0
	v_mul_f32_e32 v0, 0xbfb8aa3b, v25
	v_exp_f32_e32 v0, v0
	v_pk_fma_f32 v[32:33], v[26:27], s[74:75], v[12:13] op_sel_hi:[1,0,0]
	v_lshlrev_b32_e32 v22, 16, v4
	v_pk_fma_f32 v[32:33], v[26:27], v[32:33], s[84:85] op_sel_hi:[1,1,0]
	v_add_f32_e32 v0, 1.0, v0
	v_pk_fma_f32 v[32:33], v[26:27], v[32:33], s[86:87] op_sel_hi:[1,1,0]
	v_rcp_f32_e32 v31, v0
	v_pk_fma_f32 v[32:33], v[26:27], v[32:33], s[24:25] op_sel_hi:[1,1,0]
	v_and_b32_e32 v23, 0xffff0000, v4
	v_pk_mul_f32 v[26:27], v[26:27], v[32:33]
	v_lshlrev_b32_e32 v8, 16, v9
	v_pk_mul_f32 v[26:27], v[28:29], v[26:27]
	v_and_b32_e32 v9, 0xffff0000, v9
	v_pk_mul_f32 v[28:29], v[26:27], v[20:21]
	v_pk_fma_f32 v[20:21], v[26:27], v[20:21], v[20:21] neg_lo:[1,0,0] neg_hi:[1,0,0]
	v_lshlrev_b32_e32 v4, 16, v5
	v_cndmask_b32_e64 v21, v21, v29, s[0:1]
	v_cndmask_b32_e32 v20, v20, v28, vcc
	v_pk_mul_f32 v[20:21], v[20:21], v[22:23]
	v_pk_mul_f32 v[22:23], v[30:31], v[24:25]
	v_and_b32_e32 v5, 0xffff0000, v5
	v_pk_mul_f32 v[20:21], v[22:23], v[20:21]
	s_nop 0
	v_cvt_pk_bf16_f32 v0, v20, v21
	v_lshlrev_b32_e32 v20, 16, v1
	v_and_b32_e32 v21, 0xffff0000, v1
	v_fma_f32 v1, |v20|, s85, 1.0
	v_pk_mul_f32 v[24:25], v[20:21], v[20:21]
	v_rcp_f32_e32 v22, v1
	v_mul_f32_e32 v1, 0xbf38aa3b, v24
	v_exp_f32_e32 v24, v1
	v_mul_f32_e32 v1, 0xbfb8aa3b, v8
	v_exp_f32_e32 v1, v1
	v_cmp_gt_f32_e32 vcc, 0, v20
	v_cmp_gt_f32_e64 s[0:1], 0, v21
	v_add_f32_e32 v1, 1.0, v1
	v_rcp_f32_e32 v26, v1
	v_fma_f32 v1, |v21|, s85, 1.0
	v_rcp_f32_e32 v23, v1
	v_mul_f32_e32 v1, 0xbf38aa3b, v25
	v_exp_f32_e32 v25, v1
	v_mul_f32_e32 v1, 0xbfb8aa3b, v9
	v_exp_f32_e32 v1, v1
	v_pk_fma_f32 v[28:29], v[22:23], s[74:75], v[12:13] op_sel_hi:[1,0,0]
	v_add_f32_e32 v1, 1.0, v1
	v_pk_fma_f32 v[28:29], v[22:23], v[28:29], s[84:85] op_sel_hi:[1,1,0]
	v_rcp_f32_e32 v27, v1
	v_pk_fma_f32 v[28:29], v[22:23], v[28:29], s[86:87] op_sel_hi:[1,1,0]
	v_pk_mul_f32 v[8:9], v[26:27], v[8:9]
	v_pk_fma_f32 v[28:29], v[22:23], v[28:29], s[24:25] op_sel_hi:[1,1,0]
	s_nop 0
	v_pk_mul_f32 v[22:23], v[22:23], v[28:29]
	s_nop 0
	v_pk_mul_f32 v[22:23], v[24:25], v[22:23]
	s_nop 0
	v_pk_mul_f32 v[24:25], v[22:23], v[20:21]
	v_pk_fma_f32 v[20:21], v[22:23], v[20:21], v[20:21] neg_lo:[1,0,0] neg_hi:[1,0,0]
	s_nop 0
	v_cndmask_b32_e64 v21, v21, v25, s[0:1]
	v_cndmask_b32_e32 v20, v20, v24, vcc
	v_pk_mul_f32 v[4:5], v[20:21], v[4:5]
	v_lshlrev_b32_e32 v20, 16, v10
	v_pk_mul_f32 v[4:5], v[8:9], v[4:5]
	v_and_b32_e32 v21, 0xffff0000, v10
	v_cvt_pk_bf16_f32 v1, v4, v5
	v_lshlrev_b32_e32 v4, 16, v2
	v_and_b32_e32 v5, 0xffff0000, v2
	v_fma_f32 v2, |v4|, s85, 1.0
	v_pk_mul_f32 v[24:25], v[4:5], v[4:5]
	v_rcp_f32_e32 v22, v2
	v_mul_f32_e32 v2, 0xbf38aa3b, v24
	v_exp_f32_e32 v24, v2
	v_mul_f32_e32 v2, 0xbfb8aa3b, v20
	v_exp_f32_e32 v2, v2
	v_cmp_gt_f32_e32 vcc, 0, v4
	v_cmp_gt_f32_e64 s[0:1], 0, v5
	v_lshlrev_b32_e32 v8, 16, v6
	v_add_f32_e32 v2, 1.0, v2
	v_rcp_f32_e32 v26, v2
	v_fma_f32 v2, |v5|, s85, 1.0
	v_rcp_f32_e32 v23, v2
	v_mul_f32_e32 v2, 0xbf38aa3b, v25
	v_exp_f32_e32 v25, v2
	v_mul_f32_e32 v2, 0xbfb8aa3b, v21
	v_exp_f32_e32 v2, v2
	v_pk_fma_f32 v[28:29], v[22:23], s[74:75], v[12:13] op_sel_hi:[1,0,0]
	v_and_b32_e32 v9, 0xffff0000, v6
	v_pk_fma_f32 v[28:29], v[22:23], v[28:29], s[84:85] op_sel_hi:[1,1,0]
	v_add_f32_e32 v2, 1.0, v2
	v_pk_fma_f32 v[28:29], v[22:23], v[28:29], s[86:87] op_sel_hi:[1,1,0]
	v_rcp_f32_e32 v27, v2
	v_pk_fma_f32 v[28:29], v[22:23], v[28:29], s[24:25] op_sel_hi:[1,1,0]
	v_lshlrev_b32_e32 v6, 16, v7
	v_pk_mul_f32 v[22:23], v[22:23], v[28:29]
	v_and_b32_e32 v7, 0xffff0000, v7
	v_pk_mul_f32 v[22:23], v[24:25], v[22:23]
	s_nop 0
	v_pk_mul_f32 v[24:25], v[22:23], v[4:5]
	v_pk_fma_f32 v[4:5], v[22:23], v[4:5], v[4:5] neg_lo:[1,0,0] neg_hi:[1,0,0]
	s_nop 0
	v_cndmask_b32_e64 v5, v5, v25, s[0:1]
	v_cndmask_b32_e32 v4, v4, v24, vcc
	v_pk_mul_f32 v[4:5], v[4:5], v[8:9]
	v_pk_mul_f32 v[8:9], v[26:27], v[20:21]
	s_nop 0
	v_pk_mul_f32 v[4:5], v[8:9], v[4:5]
	v_lshlrev_b32_e32 v8, 16, v11
	v_cvt_pk_bf16_f32 v2, v4, v5
	v_lshlrev_b32_e32 v4, 16, v3
	v_and_b32_e32 v5, 0xffff0000, v3
	v_fma_f32 v3, |v4|, s85, 1.0
	v_pk_mul_f32 v[20:21], v[4:5], v[4:5]
	v_rcp_f32_e32 v10, v3
	v_mul_f32_e32 v3, 0xbf38aa3b, v20
	v_exp_f32_e32 v20, v3
	v_mul_f32_e32 v3, 0xbfb8aa3b, v8
	v_exp_f32_e32 v3, v3
	v_and_b32_e32 v9, 0xffff0000, v11
	v_cmp_gt_f32_e32 vcc, 0, v4
	v_cmp_gt_f32_e64 s[0:1], 0, v5
	v_add_f32_e32 v3, 1.0, v3
	v_rcp_f32_e32 v22, v3
	v_fma_f32 v3, |v5|, s85, 1.0
	v_rcp_f32_e32 v11, v3
	v_mul_f32_e32 v3, 0xbf38aa3b, v21
	v_exp_f32_e32 v21, v3
	v_mul_f32_e32 v3, 0xbfb8aa3b, v9
	v_exp_f32_e32 v3, v3
	v_pk_fma_f32 v[24:25], v[10:11], s[74:75], v[12:13] op_sel_hi:[1,0,0]
	v_add_f32_e32 v3, 1.0, v3
	v_pk_fma_f32 v[24:25], v[10:11], v[24:25], s[84:85] op_sel_hi:[1,1,0]
	v_rcp_f32_e32 v23, v3
	v_pk_fma_f32 v[24:25], v[10:11], v[24:25], s[86:87] op_sel_hi:[1,1,0]
	s_nop 0
	v_pk_fma_f32 v[24:25], v[10:11], v[24:25], s[24:25] op_sel_hi:[1,1,0]
	s_nop 0
	v_pk_mul_f32 v[10:11], v[10:11], v[24:25]
	s_nop 0
	v_pk_mul_f32 v[10:11], v[20:21], v[10:11]
	s_nop 0
	v_pk_mul_f32 v[20:21], v[10:11], v[4:5]
	v_pk_fma_f32 v[4:5], v[10:11], v[4:5], v[4:5] neg_lo:[1,0,0] neg_hi:[1,0,0]
	s_nop 0
	v_cndmask_b32_e64 v5, v5, v21, s[0:1]
	v_cndmask_b32_e32 v4, v4, v20, vcc
	v_pk_mul_f32 v[4:5], v[4:5], v[6:7]
	v_pk_mul_f32 v[6:7], v[22:23], v[8:9]
	s_mov_b32 s0, 0x1a000
	v_pk_mul_f32 v[4:5], v[6:7], v[4:5]
	s_nop 0
	v_cvt_pk_bf16_f32 v3, v4, v5
	global_store_dwordx4 v[18:19], v[0:3], off offset:2048
	s_nop 1
	v_add_co_u32_e32 v0, vcc, s0, v14
	s_mov_b32 s0, 0x1b000
	s_nop 0
	v_addc_co_u32_e32 v1, vcc, 0, v15, vcc
	v_add_co_u32_e32 v4, vcc, s0, v14
	s_mov_b32 s0, 0x19000
	s_nop 0
	v_addc_co_u32_e32 v5, vcc, 0, v15, vcc
	s_waitcnt vmcnt(7)
	v_mov_b64_e32 v[0:1], v[120:121]
	v_mov_b64_e32 v[2:3], v[122:123]
	v_add_co_u32_e32 v14, vcc, s0, v14
	v_mov_b64_e32 v[4:5], v[124:125]
	v_mov_b64_e32 v[6:7], v[126:127]
	s_nop 0
	v_addc_co_u32_e32 v15, vcc, 0, v15, vcc
	v_mov_b64_e32 v[8:9], v[128:129]
	v_mov_b64_e32 v[10:11], v[130:131]
	v_lshlrev_b32_e32 v18, 16, v0
	v_and_b32_e32 v19, 0xffff0000, v0
	v_fma_f32 v0, |v18|, s85, 1.0
	v_pk_mul_f32 v[26:27], v[18:19], v[18:19]
	v_rcp_f32_e32 v24, v0
	v_mul_f32_e32 v0, 0xbf38aa3b, v26
	v_lshlrev_b32_e32 v22, 16, v8
	v_exp_f32_e32 v26, v0
	v_mul_f32_e32 v0, 0xbfb8aa3b, v22
	v_exp_f32_e32 v0, v0
	v_and_b32_e32 v23, 0xffff0000, v8
	v_cmp_gt_f32_e32 vcc, 0, v18
	v_cmp_gt_f32_e64 s[0:1], 0, v19
	v_add_f32_e32 v0, 1.0, v0
	v_rcp_f32_e32 v28, v0
	v_fma_f32 v0, |v19|, s85, 1.0
	v_rcp_f32_e32 v25, v0
	v_mul_f32_e32 v0, 0xbf38aa3b, v27
	v_exp_f32_e32 v27, v0
	v_mul_f32_e32 v0, 0xbfb8aa3b, v23
	v_exp_f32_e32 v0, v0
	v_pk_fma_f32 v[30:31], v[24:25], s[74:75], v[12:13] op_sel_hi:[1,0,0]
	v_lshlrev_b32_e32 v20, 16, v4
	v_pk_fma_f32 v[30:31], v[24:25], v[30:31], s[84:85] op_sel_hi:[1,1,0]
	v_add_f32_e32 v0, 1.0, v0
	v_pk_fma_f32 v[30:31], v[24:25], v[30:31], s[86:87] op_sel_hi:[1,1,0]
	v_rcp_f32_e32 v29, v0
	v_pk_fma_f32 v[30:31], v[24:25], v[30:31], s[24:25] op_sel_hi:[1,1,0]
	v_and_b32_e32 v21, 0xffff0000, v4
	v_pk_mul_f32 v[24:25], v[24:25], v[30:31]
	v_lshlrev_b32_e32 v8, 16, v9
	v_pk_mul_f32 v[24:25], v[26:27], v[24:25]
	v_and_b32_e32 v9, 0xffff0000, v9
	v_pk_mul_f32 v[26:27], v[24:25], v[18:19]
	v_pk_fma_f32 v[18:19], v[24:25], v[18:19], v[18:19] neg_lo:[1,0,0] neg_hi:[1,0,0]
	v_lshlrev_b32_e32 v4, 16, v5
	v_cndmask_b32_e64 v19, v19, v27, s[0:1]
	v_cndmask_b32_e32 v18, v18, v26, vcc
	v_pk_mul_f32 v[18:19], v[18:19], v[20:21]
	v_pk_mul_f32 v[20:21], v[28:29], v[22:23]
	v_and_b32_e32 v5, 0xffff0000, v5
	v_pk_mul_f32 v[18:19], v[20:21], v[18:19]
	s_nop 0
	v_cvt_pk_bf16_f32 v0, v18, v19
	v_lshlrev_b32_e32 v18, 16, v1
	v_and_b32_e32 v19, 0xffff0000, v1
	v_fma_f32 v1, |v18|, s85, 1.0
	v_pk_mul_f32 v[22:23], v[18:19], v[18:19]
	v_rcp_f32_e32 v20, v1
	v_mul_f32_e32 v1, 0xbf38aa3b, v22
	v_exp_f32_e32 v22, v1
	v_mul_f32_e32 v1, 0xbfb8aa3b, v8
	v_exp_f32_e32 v1, v1
	v_cmp_gt_f32_e32 vcc, 0, v18
	v_cmp_gt_f32_e64 s[0:1], 0, v19
	v_add_f32_e32 v1, 1.0, v1
	v_rcp_f32_e32 v24, v1
	v_fma_f32 v1, |v19|, s85, 1.0
	v_rcp_f32_e32 v21, v1
	v_mul_f32_e32 v1, 0xbf38aa3b, v23
	v_exp_f32_e32 v23, v1
	v_mul_f32_e32 v1, 0xbfb8aa3b, v9
	v_exp_f32_e32 v1, v1
	v_pk_fma_f32 v[26:27], v[20:21], s[74:75], v[12:13] op_sel_hi:[1,0,0]
	v_add_f32_e32 v1, 1.0, v1
	v_pk_fma_f32 v[26:27], v[20:21], v[26:27], s[84:85] op_sel_hi:[1,1,0]
	v_rcp_f32_e32 v25, v1
	v_pk_fma_f32 v[26:27], v[20:21], v[26:27], s[86:87] op_sel_hi:[1,1,0]
	v_pk_mul_f32 v[8:9], v[24:25], v[8:9]
	v_pk_fma_f32 v[26:27], v[20:21], v[26:27], s[24:25] op_sel_hi:[1,1,0]
	s_nop 0
	v_pk_mul_f32 v[20:21], v[20:21], v[26:27]
	s_nop 0
	v_pk_mul_f32 v[20:21], v[22:23], v[20:21]
	s_nop 0
	v_pk_mul_f32 v[22:23], v[20:21], v[18:19]
	v_pk_fma_f32 v[18:19], v[20:21], v[18:19], v[18:19] neg_lo:[1,0,0] neg_hi:[1,0,0]
	s_nop 0
	v_cndmask_b32_e64 v19, v19, v23, s[0:1]
	v_cndmask_b32_e32 v18, v18, v22, vcc
	v_pk_mul_f32 v[4:5], v[18:19], v[4:5]
	v_lshlrev_b32_e32 v18, 16, v10
	v_pk_mul_f32 v[4:5], v[8:9], v[4:5]
	v_and_b32_e32 v19, 0xffff0000, v10
	v_cvt_pk_bf16_f32 v1, v4, v5
	v_lshlrev_b32_e32 v4, 16, v2
	v_and_b32_e32 v5, 0xffff0000, v2
	v_fma_f32 v2, |v4|, s85, 1.0
	v_pk_mul_f32 v[22:23], v[4:5], v[4:5]
	v_rcp_f32_e32 v20, v2
	v_mul_f32_e32 v2, 0xbf38aa3b, v22
	v_exp_f32_e32 v22, v2
	v_mul_f32_e32 v2, 0xbfb8aa3b, v18
	v_exp_f32_e32 v2, v2
	v_cmp_gt_f32_e32 vcc, 0, v4
	v_cmp_gt_f32_e64 s[0:1], 0, v5
	v_lshlrev_b32_e32 v8, 16, v6
	v_add_f32_e32 v2, 1.0, v2
	v_rcp_f32_e32 v24, v2
	v_fma_f32 v2, |v5|, s85, 1.0
	v_rcp_f32_e32 v21, v2
	v_mul_f32_e32 v2, 0xbf38aa3b, v23
	v_exp_f32_e32 v23, v2
	v_mul_f32_e32 v2, 0xbfb8aa3b, v19
	v_exp_f32_e32 v2, v2
	v_pk_fma_f32 v[26:27], v[20:21], s[74:75], v[12:13] op_sel_hi:[1,0,0]
	v_and_b32_e32 v9, 0xffff0000, v6
	v_pk_fma_f32 v[26:27], v[20:21], v[26:27], s[84:85] op_sel_hi:[1,1,0]
	v_add_f32_e32 v2, 1.0, v2
	v_pk_fma_f32 v[26:27], v[20:21], v[26:27], s[86:87] op_sel_hi:[1,1,0]
	v_rcp_f32_e32 v25, v2
	v_pk_fma_f32 v[26:27], v[20:21], v[26:27], s[24:25] op_sel_hi:[1,1,0]
	v_lshlrev_b32_e32 v6, 16, v7
	v_pk_mul_f32 v[20:21], v[20:21], v[26:27]
	v_and_b32_e32 v7, 0xffff0000, v7
	v_pk_mul_f32 v[20:21], v[22:23], v[20:21]
	s_nop 0
	v_pk_mul_f32 v[22:23], v[20:21], v[4:5]
	v_pk_fma_f32 v[4:5], v[20:21], v[4:5], v[4:5] neg_lo:[1,0,0] neg_hi:[1,0,0]
	s_nop 0
	v_cndmask_b32_e64 v5, v5, v23, s[0:1]
	v_cndmask_b32_e32 v4, v4, v22, vcc
	v_pk_mul_f32 v[4:5], v[4:5], v[8:9]
	v_pk_mul_f32 v[8:9], v[24:25], v[18:19]
	s_nop 0
	v_pk_mul_f32 v[4:5], v[8:9], v[4:5]
	v_lshlrev_b32_e32 v8, 16, v11
	v_cvt_pk_bf16_f32 v2, v4, v5
	v_lshlrev_b32_e32 v4, 16, v3
	v_and_b32_e32 v5, 0xffff0000, v3
	v_fma_f32 v3, |v4|, s85, 1.0
	v_pk_mul_f32 v[18:19], v[4:5], v[4:5]
	v_rcp_f32_e32 v10, v3
	v_mul_f32_e32 v3, 0xbf38aa3b, v18
	v_exp_f32_e32 v18, v3
	v_mul_f32_e32 v3, 0xbfb8aa3b, v8
	v_exp_f32_e32 v3, v3
	v_and_b32_e32 v9, 0xffff0000, v11
	v_cmp_gt_f32_e32 vcc, 0, v4
	v_cmp_gt_f32_e64 s[0:1], 0, v5
	v_add_f32_e32 v3, 1.0, v3
	v_rcp_f32_e32 v20, v3
	v_fma_f32 v3, |v5|, s85, 1.0
	v_rcp_f32_e32 v11, v3
	v_mul_f32_e32 v3, 0xbf38aa3b, v19
	v_exp_f32_e32 v19, v3
	v_mul_f32_e32 v3, 0xbfb8aa3b, v9
	v_exp_f32_e32 v3, v3
	v_pk_fma_f32 v[12:13], v[10:11], s[74:75], v[12:13] op_sel_hi:[1,0,0]
	v_add_f32_e32 v3, 1.0, v3
	v_pk_fma_f32 v[12:13], v[10:11], v[12:13], s[84:85] op_sel_hi:[1,1,0]
	v_rcp_f32_e32 v21, v3
	v_pk_fma_f32 v[12:13], v[10:11], v[12:13], s[86:87] op_sel_hi:[1,1,0]
	s_nop 0
	v_pk_fma_f32 v[12:13], v[10:11], v[12:13], s[24:25] op_sel_hi:[1,1,0]
	s_nop 0
	v_pk_mul_f32 v[10:11], v[10:11], v[12:13]
	s_nop 0
	v_pk_mul_f32 v[10:11], v[18:19], v[10:11]
	s_nop 0
	v_pk_mul_f32 v[12:13], v[10:11], v[4:5]
	v_pk_fma_f32 v[4:5], v[10:11], v[4:5], v[4:5] neg_lo:[1,0,0] neg_hi:[1,0,0]
	s_nop 0
	v_cndmask_b32_e64 v5, v5, v13, s[0:1]
	v_cndmask_b32_e32 v4, v4, v12, vcc
	v_pk_mul_f32 v[4:5], v[4:5], v[6:7]
	v_pk_mul_f32 v[6:7], v[20:21], v[8:9]
	s_nop 0
	v_pk_mul_f32 v[4:5], v[6:7], v[4:5]
	s_nop 0
	v_cvt_pk_bf16_f32 v3, v4, v5
	global_store_dwordx4 v[14:15], v[0:3], off
	s_branch .LBB0_1092
